# SGPR-base LDS-DMA addressing (no per-DMA VALU address adds) in the other five K-loops (P1b, SchedA/B/C, Sched1a)
# baseline (speedup 1.0000x reference)
; #define G_STAGE(bufoff, gbase, voff) do { _Pragma("unroll") for (int _i = 0; _i < 2; ++_i) \
;         __builtin_amdgcn_global_load_lds((const unsigned*)((const char*)(gbase) + (voff)[_i]), (LAS unsigned*)(lds + (bufoff) + ldsw + _i * 8192), 16, 0, 0); } while (0)
; #define G_WAIT_V(n) asm volatile("s_waitcnt vmcnt(" #n ")" ::: "memory")
; #define G_WAIT_L(n) asm volatile("s_waitcnt lgkmcnt(" #n ")" ::: "memory")
; #define G_BAR __builtin_amdgcn_s_barrier()
; #define G_SCHED __builtin_amdgcn_sched_barrier(0)
; template <int MODE  , class Epi, class Sched>
; __device__ __forceinline__ void gemm_phase(LAS unsigned char* lds, const GemmDesc g, const Sched& S, const Epi& E) {
;     ...
;             G_LDB(B0, 0, 0); G_SCHED; G_LDA(At, 0, 0); G_STAGE(G_SA(1, 1), a1 + hstepA, voffA);
;             G_WAIT_L(8); G_BAR; G_WAIT_L(0); G_MMA(0, 0, At, B0); G_BAR; G_SCHED;
;             G_LDB(B1, 0, 1); G_STAGE(G_SB(0, 0), b2, voffB);
;             G_BAR; G_WAIT_L(0); G_MMA(0, 1, At, B1); G_BAR;
;             G_LDA(At, 0, 1); G_STAGE(G_SA(0, 0), a2, voffA);
;             G_BAR; G_WAIT_L(0); G_MMA(1, 0, At, B0); G_BAR; G_SCHED;
;             G_STAGE(G_SB(0, 1), b2 + hstepB, voffB);
;             G_WAIT_V(6); G_BAR; G_MMA(1, 1, At, B1); G_BAR;
.Lnodb_p1b:
.LBB0_737:
	ds_read_b128 v[2:5], v168
	ds_read_b128 v[6:9], v168 offset:1024
	ds_read_b128 v[10:13], v168 offset:2048
	ds_read_b128 v[14:17], v168 offset:3072
	s_add_u32 s46, s50, 0x100
	s_addc_u32 s47, s51, 0
	s_cmp_eq_u32 s79, 12
	s_cselect_b32 s55, s45, s47
	s_cselect_b32 s54, s44, s46
	s_cselect_b32 s53, s3, s78
	s_cselect_b32 s52, s2, s77
	s_add_u32 s98, s50, 0x44080
	s_addc_u32 s99, s51, 0
	s_add_i32 m0, s62, 0xc000
	ds_read_b128 v[174:177], v169
	ds_read_b128 v[178:181], v169 offset:1024
	ds_read_b128 v[182:185], v169 offset:2048
	ds_read_b128 v[186:189], v169 offset:3072
	ds_read_b128 v[192:195], v169 offset:4096
	ds_read_b128 v[196:199], v169 offset:5120
	ds_read_b128 v[200:203], v169 offset:6144
	ds_read_b128 v[204:207], v169 offset:7168
	global_load_lds_dwordx4 v152, s[98:99]
	s_add_i32 m0, s62, 0xe000
	s_nop 0
	global_load_lds_dwordx4 v148, s[98:99]
	s_waitcnt lgkmcnt(8)
	s_barrier
	s_waitcnt lgkmcnt(0)
	s_setprio 1
	s_waitcnt lgkmcnt(0)
	v_mfma_scale_f32_16x16x128_f8f6f4 v[142:145], v[2:9], v[174:181], v[142:145], v170, v170 op_sel_hi:[0,0,0]
	v_mfma_scale_f32_16x16x128_f8f6f4 v[138:141], v[10:17], v[174:181], v[138:141], v170, v170 op_sel_hi:[0,0,0]
	v_mfma_scale_f32_16x16x128_f8f6f4 v[126:129], v[2:9], v[182:189], v[126:129], v170, v170 op_sel_hi:[0,0,0]
	v_mfma_scale_f32_16x16x128_f8f6f4 v[122:125], v[10:17], v[182:189], v[122:125], v170, v170 op_sel_hi:[0,0,0]
	v_mfma_scale_f32_16x16x128_f8f6f4 v[110:113], v[2:9], v[192:199], v[110:113], v170, v170 op_sel_hi:[0,0,0]
	v_mfma_scale_f32_16x16x128_f8f6f4 v[106:109], v[10:17], v[192:199], v[106:109], v170, v170 op_sel_hi:[0,0,0]
	v_mfma_scale_f32_16x16x128_f8f6f4 v[94:97], v[2:9], v[200:207], v[94:97], v170, v170 op_sel_hi:[0,0,0]
	v_mfma_scale_f32_16x16x128_f8f6f4 v[90:93], v[10:17], v[200:207], v[90:93], v170, v170 op_sel_hi:[0,0,0]
	s_setprio 0
	s_barrier
	s_add_i32 s0, s69, s60
	s_mov_b32 m0, s0
	ds_read_b128 v[208:211], v171
	ds_read_b128 v[212:215], v171 offset:1024
	ds_read_b128 v[216:219], v171 offset:2048
	ds_read_b128 v[220:223], v171 offset:3072
	global_load_lds_dwordx4 v150, s[52:53]
	s_add_i32 m0, s0, 0x2000
	s_nop 0
	global_load_lds_dwordx4 v146, s[52:53]
	s_barrier
	s_waitcnt lgkmcnt(0)
	s_setprio 1
	s_waitcnt lgkmcnt(0)
	v_mfma_scale_f32_16x16x128_f8f6f4 v[134:137], v[208:215], v[174:181], v[134:137], v170, v170 op_sel_hi:[0,0,0]
	v_mfma_scale_f32_16x16x128_f8f6f4 v[130:133], v[216:223], v[174:181], v[130:133], v170, v170 op_sel_hi:[0,0,0]
	v_mfma_scale_f32_16x16x128_f8f6f4 v[118:121], v[208:215], v[182:189], v[118:121], v170, v170 op_sel_hi:[0,0,0]
	v_mfma_scale_f32_16x16x128_f8f6f4 v[114:117], v[216:223], v[182:189], v[114:117], v170, v170 op_sel_hi:[0,0,0]
	v_mfma_scale_f32_16x16x128_f8f6f4 v[102:105], v[208:215], v[192:199], v[102:105], v170, v170 op_sel_hi:[0,0,0]
	v_mfma_scale_f32_16x16x128_f8f6f4 v[98:101], v[216:223], v[192:199], v[98:101], v170, v170 op_sel_hi:[0,0,0]
	v_mfma_scale_f32_16x16x128_f8f6f4 v[86:89], v[208:215], v[200:207], v[86:89], v170, v170 op_sel_hi:[0,0,0]
	v_mfma_scale_f32_16x16x128_f8f6f4 v[82:85], v[216:223], v[200:207], v[82:85], v170, v170 op_sel_hi:[0,0,0]
	s_setprio 0
	s_mov_b32 m0, s62
	s_barrier
	ds_read_b128 v[174:177], v169 offset:16384
	ds_read_b128 v[178:181], v169 offset:17408
	ds_read_b128 v[182:185], v169 offset:18432
	ds_read_b128 v[186:189], v169 offset:19456
	ds_read_b128 v[192:195], v169 offset:20480
	ds_read_b128 v[196:199], v169 offset:21504
	ds_read_b128 v[200:203], v169 offset:22528
	ds_read_b128 v[204:207], v169 offset:23552
	global_load_lds_dwordx4 v152, s[54:55]
	s_mov_b32 m0, s63
	s_nop 0
	global_load_lds_dwordx4 v148, s[54:55]
	s_barrier
	s_waitcnt lgkmcnt(0)
	s_setprio 1
	s_waitcnt lgkmcnt(0)
	v_mfma_scale_f32_16x16x128_f8f6f4 v[78:81], v[2:9], v[174:181], v[78:81], v170, v170 op_sel_hi:[0,0,0]
	v_mfma_scale_f32_16x16x128_f8f6f4 v[74:77], v[10:17], v[174:181], v[74:77], v170, v170 op_sel_hi:[0,0,0]
	v_mfma_scale_f32_16x16x128_f8f6f4 v[62:65], v[2:9], v[182:189], v[62:65], v170, v170 op_sel_hi:[0,0,0]
	v_mfma_scale_f32_16x16x128_f8f6f4 v[58:61], v[10:17], v[182:189], v[58:61], v170, v170 op_sel_hi:[0,0,0]
	v_mfma_scale_f32_16x16x128_f8f6f4 v[46:49], v[2:9], v[192:199], v[46:49], v170, v170 op_sel_hi:[0,0,0]
	v_mfma_scale_f32_16x16x128_f8f6f4 v[42:45], v[10:17], v[192:199], v[42:45], v170, v170 op_sel_hi:[0,0,0]
	v_mfma_scale_f32_16x16x128_f8f6f4 v[30:33], v[2:9], v[200:207], v[30:33], v170, v170 op_sel_hi:[0,0,0]
	v_mfma_scale_f32_16x16x128_f8f6f4 v[26:29], v[10:17], v[200:207], v[26:29], v170, v170 op_sel_hi:[0,0,0]
	s_setprio 0
	s_barrier
	s_add_u32 s0, s52, 0x44000
	s_addc_u32 s1, s53, 0
	s_add_i32 s10, s70, s60
	s_mov_b32 m0, s10
	s_nop 0
	global_load_lds_dwordx4 v150, s[0:1]
	s_add_i32 m0, s10, 0x2000
	s_nop 0
	global_load_lds_dwordx4 v146, s[0:1]
	s_waitcnt vmcnt(6)
	s_barrier
	s_setprio 1
	v_mfma_scale_f32_16x16x128_f8f6f4 v[70:73], v[208:215], v[174:181], v[70:73], v170, v170 op_sel_hi:[0,0,0]
	v_mfma_scale_f32_16x16x128_f8f6f4 v[66:69], v[216:223], v[174:181], v[66:69], v170, v170 op_sel_hi:[0,0,0]
	v_mfma_scale_f32_16x16x128_f8f6f4 v[54:57], v[208:215], v[182:189], v[54:57], v170, v170 op_sel_hi:[0,0,0]
	v_mfma_scale_f32_16x16x128_f8f6f4 v[50:53], v[216:223], v[182:189], v[50:53], v170, v170 op_sel_hi:[0,0,0]
	v_mfma_scale_f32_16x16x128_f8f6f4 v[38:41], v[208:215], v[192:199], v[38:41], v170, v170 op_sel_hi:[0,0,0]
	v_mfma_scale_f32_16x16x128_f8f6f4 v[34:37], v[216:223], v[192:199], v[34:37], v170, v170 op_sel_hi:[0,0,0]
	v_mfma_scale_f32_16x16x128_f8f6f4 v[22:25], v[208:215], v[200:207], v[22:25], v170, v170 op_sel_hi:[0,0,0]
	v_mfma_scale_f32_16x16x128_f8f6f4 v[18:21], v[216:223], v[200:207], v[18:21], v170, v170 op_sel_hi:[0,0,0]
	s_setprio 0
	s_add_i32 s10, 0, 0x18000
	v_add_u32_e32 v14, s10, v166
	s_barrier
; #define G_STAGE(bufoff, gbase, voff) do { _Pragma("unroll") for (int _i = 0; _i < 2; ++_i) \
;         __builtin_amdgcn_global_load_lds((const unsigned*)((const char*)(gbase) + (voff)[_i]), (LAS unsigned*)(lds + (bufoff) + ldsw + _i * 8192), 16, 0, 0); } while (0)
; #define G_WAIT_V(n) asm volatile("s_waitcnt vmcnt(" #n ")" ::: "memory")
; #define G_WAIT_L(n) asm volatile("s_waitcnt lgkmcnt(" #n ")" ::: "memory")
; #define G_BAR __builtin_amdgcn_s_barrier()
; #define G_SCHED __builtin_amdgcn_sched_barrier(0)
; template <int MODE  , class Epi, class Sched>
; __device__ __forceinline__ void gemm_phase(LAS unsigned char* lds, const GemmDesc g, const Sched& S, const Epi& E) {
;     ...
;             G_LDB(B0, 1, 0); G_SCHED; G_LDA(At, 1, 0); G_STAGE(G_SA(0, 1), a2 + hstepA, voffA);
;             G_WAIT_L(8); G_BAR; G_WAIT_L(0); G_MMA(0, 0, At, B0); G_BAR; G_SCHED;
;             G_LDB(B1, 1, 1); G_STAGE(G_SB(1, 0), b3, voffB);
;             G_BAR; G_WAIT_L(0); G_MMA(0, 1, At, B1); G_BAR;
;             G_LDA(At, 1, 1); G_STAGE(G_SA(1, 0), a3, voffA);
;             G_BAR; G_WAIT_L(0); G_MMA(1, 0, At, B0); G_BAR; G_SCHED;
;             G_STAGE(G_SB(1, 1), b3 + hstepB, voffB);
;             G_WAIT_V(6); G_BAR; G_MMA(1, 1, At, B1); G_BAR;
	ds_read_b128 v[2:5], v14
	ds_read_b128 v[6:9], v14 offset:1024
	ds_read_b128 v[10:13], v14 offset:2048
	ds_read_b128 v[14:17], v14 offset:3072
	s_add_u32 s0, s54, 0x44000
	s_addc_u32 s1, s55, 0
	s_mov_b32 m0, s64
	ds_read_b128 v[174:177], v169 offset:32768
	ds_read_b128 v[178:181], v169 offset:33792
	ds_read_b128 v[182:185], v169 offset:34816
	ds_read_b128 v[186:189], v169 offset:35840
	ds_read_b128 v[192:195], v169 offset:36864
	ds_read_b128 v[196:199], v169 offset:37888
	ds_read_b128 v[200:203], v169 offset:38912
	ds_read_b128 v[204:207], v169 offset:39936
	global_load_lds_dwordx4 v152, s[0:1]
	s_mov_b32 m0, s65
	s_nop 0
	global_load_lds_dwordx4 v148, s[0:1]
	s_waitcnt lgkmcnt(8)
	s_barrier
	s_waitcnt lgkmcnt(0)
	s_setprio 1
	s_waitcnt lgkmcnt(0)
	v_mfma_scale_f32_16x16x128_f8f6f4 v[142:145], v[2:9], v[174:181], v[142:145], v170, v170 op_sel_hi:[0,0,0]
	v_mfma_scale_f32_16x16x128_f8f6f4 v[138:141], v[10:17], v[174:181], v[138:141], v170, v170 op_sel_hi:[0,0,0]
	v_mfma_scale_f32_16x16x128_f8f6f4 v[126:129], v[2:9], v[182:189], v[126:129], v170, v170 op_sel_hi:[0,0,0]
	v_mfma_scale_f32_16x16x128_f8f6f4 v[122:125], v[10:17], v[182:189], v[122:125], v170, v170 op_sel_hi:[0,0,0]
	v_mfma_scale_f32_16x16x128_f8f6f4 v[110:113], v[2:9], v[192:199], v[110:113], v170, v170 op_sel_hi:[0,0,0]
	v_mfma_scale_f32_16x16x128_f8f6f4 v[106:109], v[10:17], v[192:199], v[106:109], v170, v170 op_sel_hi:[0,0,0]
	v_mfma_scale_f32_16x16x128_f8f6f4 v[94:97], v[2:9], v[200:207], v[94:97], v170, v170 op_sel_hi:[0,0,0]
	v_mfma_scale_f32_16x16x128_f8f6f4 v[90:93], v[10:17], v[200:207], v[90:93], v170, v170 op_sel_hi:[0,0,0]
	s_setprio 0
	s_barrier
	s_add_i32 s11, 0, 0x1c000
	s_add_i32 s0, s10, s60
	v_add_u32_e32 v173, s11, v166
	s_add_u32 s98, s52, 0x80
	s_addc_u32 s99, s53, 0
	s_mov_b32 m0, s0
	ds_read_b128 v[208:211], v173
	ds_read_b128 v[212:215], v173 offset:1024
	ds_read_b128 v[216:219], v173 offset:2048
	ds_read_b128 v[220:223], v173 offset:3072
	global_load_lds_dwordx4 v150, s[98:99]
	s_add_i32 m0, s0, 0x2000
	s_nop 0
	global_load_lds_dwordx4 v146, s[98:99]
	s_barrier
	s_waitcnt lgkmcnt(0)
	s_setprio 1
	s_waitcnt lgkmcnt(0)
	v_mfma_scale_f32_16x16x128_f8f6f4 v[134:137], v[208:215], v[174:181], v[134:137], v170, v170 op_sel_hi:[0,0,0]
	v_mfma_scale_f32_16x16x128_f8f6f4 v[130:133], v[216:223], v[174:181], v[130:133], v170, v170 op_sel_hi:[0,0,0]
	v_mfma_scale_f32_16x16x128_f8f6f4 v[118:121], v[208:215], v[182:189], v[118:121], v170, v170 op_sel_hi:[0,0,0]
	v_mfma_scale_f32_16x16x128_f8f6f4 v[114:117], v[216:223], v[182:189], v[114:117], v170, v170 op_sel_hi:[0,0,0]
	v_mfma_scale_f32_16x16x128_f8f6f4 v[102:105], v[208:215], v[192:199], v[102:105], v170, v170 op_sel_hi:[0,0,0]
	v_mfma_scale_f32_16x16x128_f8f6f4 v[98:101], v[216:223], v[192:199], v[98:101], v170, v170 op_sel_hi:[0,0,0]
	v_mfma_scale_f32_16x16x128_f8f6f4 v[86:89], v[208:215], v[200:207], v[86:89], v170, v170 op_sel_hi:[0,0,0]
	v_mfma_scale_f32_16x16x128_f8f6f4 v[82:85], v[216:223], v[200:207], v[82:85], v170, v170 op_sel_hi:[0,0,0]
	s_setprio 0
	s_mov_b32 m0, s67
	s_add_u32 s98, s54, 0x80
	s_addc_u32 s99, s55, 0
	s_barrier
	ds_read_b128 v[174:177], v169 offset:49152
	ds_read_b128 v[178:181], v169 offset:50176
	ds_read_b128 v[182:185], v169 offset:51200
	ds_read_b128 v[186:189], v169 offset:52224
	ds_read_b128 v[192:195], v169 offset:53248
	ds_read_b128 v[196:199], v169 offset:54272
	ds_read_b128 v[200:203], v169 offset:55296
	ds_read_b128 v[204:207], v169 offset:56320
	global_load_lds_dwordx4 v152, s[98:99]
	s_mov_b32 m0, s68
	s_nop 0
	global_load_lds_dwordx4 v148, s[98:99]
	s_barrier
	s_waitcnt lgkmcnt(0)
	s_setprio 1
	s_waitcnt lgkmcnt(0)
	v_mfma_scale_f32_16x16x128_f8f6f4 v[78:81], v[2:9], v[174:181], v[78:81], v170, v170 op_sel_hi:[0,0,0]
	v_mfma_scale_f32_16x16x128_f8f6f4 v[74:77], v[10:17], v[174:181], v[74:77], v170, v170 op_sel_hi:[0,0,0]
	v_mfma_scale_f32_16x16x128_f8f6f4 v[62:65], v[2:9], v[182:189], v[62:65], v170, v170 op_sel_hi:[0,0,0]
	v_mfma_scale_f32_16x16x128_f8f6f4 v[58:61], v[10:17], v[182:189], v[58:61], v170, v170 op_sel_hi:[0,0,0]
	v_mfma_scale_f32_16x16x128_f8f6f4 v[46:49], v[2:9], v[192:199], v[46:49], v170, v170 op_sel_hi:[0,0,0]
	v_mfma_scale_f32_16x16x128_f8f6f4 v[42:45], v[10:17], v[192:199], v[42:45], v170, v170 op_sel_hi:[0,0,0]
	v_mfma_scale_f32_16x16x128_f8f6f4 v[30:33], v[2:9], v[200:207], v[30:33], v170, v170 op_sel_hi:[0,0,0]
	v_mfma_scale_f32_16x16x128_f8f6f4 v[26:29], v[10:17], v[200:207], v[26:29], v170, v170 op_sel_hi:[0,0,0]
	s_setprio 0
	s_barrier
	s_add_u32 s0, s52, 0x44080
	s_addc_u32 s1, s53, 0
	s_add_i32 s10, s11, s60
	s_mov_b32 m0, s10
	s_nop 0
	global_load_lds_dwordx4 v150, s[0:1]
	s_add_i32 m0, s10, 0x2000
	s_nop 0
	global_load_lds_dwordx4 v146, s[0:1]
	s_waitcnt vmcnt(6)
	s_barrier
	s_setprio 1
	v_mfma_scale_f32_16x16x128_f8f6f4 v[70:73], v[208:215], v[174:181], v[70:73], v170, v170 op_sel_hi:[0,0,0]
	s_add_i32 s79, s79, 2
	s_add_u32 s77, s77, 0x100
	s_addc_u32 s78, s78, 0
	s_cmp_gt_u32 s79, 13
	s_mov_b64 s[50:51], s[46:47]
	v_mfma_scale_f32_16x16x128_f8f6f4 v[66:69], v[216:223], v[174:181], v[66:69], v170, v170 op_sel_hi:[0,0,0]
	v_mfma_scale_f32_16x16x128_f8f6f4 v[54:57], v[208:215], v[182:189], v[54:57], v170, v170 op_sel_hi:[0,0,0]
	v_mfma_scale_f32_16x16x128_f8f6f4 v[50:53], v[216:223], v[182:189], v[50:53], v170, v170 op_sel_hi:[0,0,0]
	v_mfma_scale_f32_16x16x128_f8f6f4 v[38:41], v[208:215], v[192:199], v[38:41], v170, v170 op_sel_hi:[0,0,0]
	v_mfma_scale_f32_16x16x128_f8f6f4 v[34:37], v[216:223], v[192:199], v[34:37], v170, v170 op_sel_hi:[0,0,0]
	v_mfma_scale_f32_16x16x128_f8f6f4 v[22:25], v[208:215], v[200:207], v[22:25], v170, v170 op_sel_hi:[0,0,0]
	v_mfma_scale_f32_16x16x128_f8f6f4 v[18:21], v[216:223], v[200:207], v[18:21], v170, v170 op_sel_hi:[0,0,0]
	s_setprio 0
	s_cbranch_scc1 .Lkdone_p1b
	s_barrier
	s_branch .LBB0_737

; #define G_STAGE(bufoff, gbase, voff) do { _Pragma("unroll") for (int _i = 0; _i < 2; ++_i) \
;         __builtin_amdgcn_global_load_lds((const unsigned*)((const char*)(gbase) + (voff)[_i]), (LAS unsigned*)(lds + (bufoff) + ldsw + _i * 8192), 16, 0, 0); } while (0)
; #define G_WAIT_L(n) asm volatile("s_waitcnt lgkmcnt(" #n ")" ::: "memory")
; #define G_BAR __builtin_amdgcn_s_barrier()
; #define G_SCHED __builtin_amdgcn_sched_barrier(0)
; template <int MODE  , class Epi, class Sched>
; __device__ __forceinline__ void gemm_phase(LAS unsigned char* lds, const GemmDesc g, const Sched& S, const Epi& E) {
;     ...
;             G_LDB(B0, 0, 0); G_SCHED; G_LDA(At, 0, 0); G_STAGE(G_SA(1, 1), a1 + hstepA, voffA);
;             G_WAIT_L(8); G_BAR; G_WAIT_L(0); G_MMA(0, 0, At, B0); G_BAR; G_SCHED;
;             G_LDB(B1, 0, 1); G_STAGE(G_SB(0, 0), b2, voffB);
;             G_BAR; G_WAIT_L(0); G_MMA(0, 1, At, B1); G_BAR;
;             G_LDA(At, 0, 1); G_STAGE(G_SA(0, 0), a2, voffA);
;             G_BAR; G_WAIT_L(0); G_MMA(1, 0, At, B0); G_BAR; G_SCHED;
;             G_STAGE(G_SB(0, 1), b2 + hstepB, voffB);
.Lnodb_sa:
.LBB0_815:
	v_add_u32_e32 v142, s58, v172
	ds_read_b128 v[130:133], v142
	ds_read_b128 v[134:137], v142 offset:1024
	ds_read_b128 v[138:141], v142 offset:2048
	ds_read_b128 v[142:145], v142 offset:3072
	s_add_u32 s44, s42, 0x100
	s_addc_u32 s45, s43, 0
	s_cmp_eq_u32 s68, 12
	s_cselect_b32 s49, s35, s45
	s_cselect_b32 s48, s34, s44
	s_cselect_b32 s47, s3, s67
	s_cselect_b32 s46, s2, s21
	s_add_u32 s98, s42, 0x84080
	s_addc_u32 s99, s43, 0
	s_add_i32 m0, s52, 0xc000
	ds_read_b128 v[158:161], v174
	ds_read_b128 v[162:165], v174 offset:1024
	ds_read_b128 v[166:169], v174 offset:2048
	ds_read_b128 v[176:179], v174 offset:3072
	ds_read_b128 v[180:183], v174 offset:4096
	ds_read_b128 v[184:187], v174 offset:5120
	ds_read_b128 v[192:195], v174 offset:6144
	ds_read_b128 v[196:199], v174 offset:7168
	global_load_lds_dwordx4 v146, s[98:99]
	s_add_i32 m0, s52, 0xe000
	s_nop 0
	global_load_lds_dwordx4 v150, s[98:99]
	s_waitcnt lgkmcnt(8)
	s_barrier
	s_waitcnt lgkmcnt(0)
	s_setprio 1
	s_waitcnt lgkmcnt(0)
	v_mfma_f32_16x16x32_bf16 v[126:129], v[130:133], v[158:161], v[126:129]
	v_mfma_f32_16x16x32_bf16 v[122:125], v[138:141], v[158:161], v[122:125]
	v_mfma_f32_16x16x32_bf16 v[118:121], v[130:133], v[166:169], v[118:121]
	v_mfma_f32_16x16x32_bf16 v[114:117], v[138:141], v[166:169], v[114:117]
	v_mfma_f32_16x16x32_bf16 v[110:113], v[130:133], v[180:183], v[110:113]
	v_mfma_f32_16x16x32_bf16 v[106:109], v[138:141], v[180:183], v[106:109]
	v_mfma_f32_16x16x32_bf16 v[102:105], v[130:133], v[192:195], v[102:105]
	v_mfma_f32_16x16x32_bf16 v[98:101], v[138:141], v[192:195], v[98:101]
	v_mfma_f32_16x16x32_bf16 v[126:129], v[134:137], v[162:165], v[126:129]
	v_mfma_f32_16x16x32_bf16 v[122:125], v[142:145], v[162:165], v[122:125]
	v_mfma_f32_16x16x32_bf16 v[118:121], v[134:137], v[176:179], v[118:121]
	v_mfma_f32_16x16x32_bf16 v[114:117], v[142:145], v[176:179], v[114:117]
	v_mfma_f32_16x16x32_bf16 v[110:113], v[134:137], v[184:187], v[110:113]
	v_mfma_f32_16x16x32_bf16 v[106:109], v[142:145], v[184:187], v[106:109]
	v_mfma_f32_16x16x32_bf16 v[102:105], v[134:137], v[196:199], v[102:105]
	v_mfma_f32_16x16x32_bf16 v[98:101], v[142:145], v[196:199], v[98:101]
	s_setprio 0
	s_barrier
	v_add_u32_e32 v170, s59, v172
	s_add_i32 s0, s58, s51
	ds_read_b128 v[200:203], v170
	ds_read_b128 v[204:207], v170 offset:1024
	ds_read_b128 v[208:211], v170 offset:2048
	ds_read_b128 v[212:215], v170 offset:3072
	s_mov_b32 m0, s0
	s_nop 0
	global_load_lds_dwordx4 v148, s[46:47]
	s_add_i32 m0, s0, 0x2000
	s_nop 0
	global_load_lds_dwordx4 v152, s[46:47]
	s_barrier
	s_waitcnt lgkmcnt(0)
	s_setprio 1
	s_waitcnt lgkmcnt(0)
	v_mfma_f32_16x16x32_bf16 v[94:97], v[200:203], v[158:161], v[94:97]
	v_mfma_f32_16x16x32_bf16 v[90:93], v[208:211], v[158:161], v[90:93]
	v_mfma_f32_16x16x32_bf16 v[86:89], v[200:203], v[166:169], v[86:89]
	v_mfma_f32_16x16x32_bf16 v[82:85], v[208:211], v[166:169], v[82:85]
	v_mfma_f32_16x16x32_bf16 v[78:81], v[200:203], v[180:183], v[78:81]
	v_mfma_f32_16x16x32_bf16 v[74:77], v[208:211], v[180:183], v[74:77]
	v_mfma_f32_16x16x32_bf16 v[70:73], v[200:203], v[192:195], v[70:73]
	v_mfma_f32_16x16x32_bf16 v[66:69], v[208:211], v[192:195], v[66:69]
	v_mfma_f32_16x16x32_bf16 v[94:97], v[204:207], v[162:165], v[94:97]
	v_mfma_f32_16x16x32_bf16 v[90:93], v[212:215], v[162:165], v[90:93]
	v_mfma_f32_16x16x32_bf16 v[86:89], v[204:207], v[176:179], v[86:89]
	v_mfma_f32_16x16x32_bf16 v[82:85], v[212:215], v[176:179], v[82:85]
	v_mfma_f32_16x16x32_bf16 v[78:81], v[204:207], v[184:187], v[78:81]
	v_mfma_f32_16x16x32_bf16 v[74:77], v[212:215], v[184:187], v[74:77]
	v_mfma_f32_16x16x32_bf16 v[70:73], v[204:207], v[196:199], v[70:73]
	v_mfma_f32_16x16x32_bf16 v[66:69], v[212:215], v[196:199], v[66:69]
	s_setprio 0
	s_mov_b32 m0, s52
	s_barrier
	ds_read_b128 v[158:161], v174 offset:16384
	ds_read_b128 v[162:165], v174 offset:17408
	ds_read_b128 v[166:169], v174 offset:18432
	ds_read_b128 v[176:179], v174 offset:19456
	ds_read_b128 v[180:183], v174 offset:20480
	ds_read_b128 v[184:187], v174 offset:21504
	ds_read_b128 v[192:195], v174 offset:22528
	ds_read_b128 v[196:199], v174 offset:23552
	global_load_lds_dwordx4 v146, s[48:49]
	s_mov_b32 m0, s53
	s_nop 0
	global_load_lds_dwordx4 v150, s[48:49]
	s_barrier
	s_waitcnt lgkmcnt(0)
	s_setprio 1
	s_waitcnt lgkmcnt(0)
	v_mfma_f32_16x16x32_bf16 v[62:65], v[130:133], v[158:161], v[62:65]
	v_mfma_f32_16x16x32_bf16 v[58:61], v[138:141], v[158:161], v[58:61]
	v_mfma_f32_16x16x32_bf16 v[54:57], v[130:133], v[166:169], v[54:57]
	v_mfma_f32_16x16x32_bf16 v[50:53], v[138:141], v[166:169], v[50:53]
	v_mfma_f32_16x16x32_bf16 v[46:49], v[130:133], v[180:183], v[46:49]
	v_mfma_f32_16x16x32_bf16 v[42:45], v[138:141], v[180:183], v[42:45]
	v_mfma_f32_16x16x32_bf16 v[38:41], v[130:133], v[192:195], v[38:41]
	v_mfma_f32_16x16x32_bf16 v[34:37], v[138:141], v[192:195], v[34:37]
	v_mfma_f32_16x16x32_bf16 v[62:65], v[134:137], v[162:165], v[62:65]
	v_mfma_f32_16x16x32_bf16 v[58:61], v[142:145], v[162:165], v[58:61]
	v_mfma_f32_16x16x32_bf16 v[54:57], v[134:137], v[176:179], v[54:57]
	v_mfma_f32_16x16x32_bf16 v[50:53], v[142:145], v[176:179], v[50:53]
	v_mfma_f32_16x16x32_bf16 v[46:49], v[134:137], v[184:187], v[46:49]
	v_mfma_f32_16x16x32_bf16 v[42:45], v[142:145], v[184:187], v[42:45]
	v_mfma_f32_16x16x32_bf16 v[38:41], v[134:137], v[196:199], v[38:41]
	v_mfma_f32_16x16x32_bf16 v[34:37], v[142:145], v[196:199], v[34:37]
	s_setprio 0
	s_barrier
	s_add_u32 s0, s46, 0x84000
	s_addc_u32 s1, s47, 0
	s_add_i32 s10, s59, s51
	s_mov_b32 m0, s10
	s_nop 0
	global_load_lds_dwordx4 v148, s[0:1]
	s_add_i32 m0, s10, 0x2000
	s_nop 0
	global_load_lds_dwordx4 v152, s[0:1]
	s_waitcnt vmcnt(6)
	s_barrier
; #define G_STAGE(bufoff, gbase, voff) do { _Pragma("unroll") for (int _i = 0; _i < 2; ++_i) \
;         __builtin_amdgcn_global_load_lds((const unsigned*)((const char*)(gbase) + (voff)[_i]), (LAS unsigned*)(lds + (bufoff) + ldsw + _i * 8192), 16, 0, 0); } while (0)
; #define G_WAIT_V(n) asm volatile("s_waitcnt vmcnt(" #n ")" ::: "memory")
; #define G_WAIT_L(n) asm volatile("s_waitcnt lgkmcnt(" #n ")" ::: "memory")
; #define G_BAR __builtin_amdgcn_s_barrier()
; #define G_SCHED __builtin_amdgcn_sched_barrier(0)
; template <int MODE  , class Epi, class Sched>
; __device__ __forceinline__ void gemm_phase(LAS unsigned char* lds, const GemmDesc g, const Sched& S, const Epi& E) {
;     ...
;             G_WAIT_V(6); G_BAR; G_MMA(1, 1, At, B1); G_BAR;
;             G_LDB(B0, 1, 0); G_SCHED; G_LDA(At, 1, 0); G_STAGE(G_SA(0, 1), a2 + hstepA, voffA);
;             G_WAIT_L(8); G_BAR; G_WAIT_L(0); G_MMA(0, 0, At, B0); G_BAR; G_SCHED;
;             G_LDB(B1, 1, 1); G_STAGE(G_SB(1, 0), b3, voffB);
	s_setprio 1
	v_mfma_f32_16x16x32_bf16 v[30:33], v[200:203], v[158:161], v[30:33]
	v_mfma_f32_16x16x32_bf16 v[26:29], v[208:211], v[158:161], v[26:29]
	v_mfma_f32_16x16x32_bf16 v[22:25], v[200:203], v[166:169], v[22:25]
	v_mfma_f32_16x16x32_bf16 v[18:21], v[208:211], v[166:169], v[18:21]
	v_mfma_f32_16x16x32_bf16 v[14:17], v[200:203], v[180:183], v[14:17]
	v_mfma_f32_16x16x32_bf16 v[10:13], v[208:211], v[180:183], v[10:13]
	v_mfma_f32_16x16x32_bf16 v[6:9], v[200:203], v[192:195], v[6:9]
	v_mfma_f32_16x16x32_bf16 v[2:5], v[208:211], v[192:195], v[2:5]
	v_mfma_f32_16x16x32_bf16 v[30:33], v[204:207], v[162:165], v[30:33]
	v_mfma_f32_16x16x32_bf16 v[26:29], v[212:215], v[162:165], v[26:29]
	v_mfma_f32_16x16x32_bf16 v[22:25], v[204:207], v[176:179], v[22:25]
	v_mfma_f32_16x16x32_bf16 v[18:21], v[212:215], v[176:179], v[18:21]
	v_mfma_f32_16x16x32_bf16 v[14:17], v[204:207], v[184:187], v[14:17]
	v_mfma_f32_16x16x32_bf16 v[10:13], v[212:215], v[184:187], v[10:13]
	v_mfma_f32_16x16x32_bf16 v[6:9], v[204:207], v[196:199], v[6:9]
	v_mfma_f32_16x16x32_bf16 v[2:5], v[212:215], v[196:199], v[2:5]
	s_setprio 0
	s_add_i32 s10, 0, 0x18000
	v_add_u32_e32 v142, s10, v172
	s_barrier
	ds_read_b128 v[130:133], v142
	ds_read_b128 v[134:137], v142 offset:1024
	ds_read_b128 v[138:141], v142 offset:2048
	ds_read_b128 v[142:145], v142 offset:3072
	s_add_u32 s0, s48, 0x84000
	s_addc_u32 s1, s49, 0
	s_mov_b32 m0, s54
	ds_read_b128 v[158:161], v174 offset:32768
	ds_read_b128 v[162:165], v174 offset:33792
	ds_read_b128 v[166:169], v174 offset:34816
	ds_read_b128 v[176:179], v174 offset:35840
	ds_read_b128 v[180:183], v174 offset:36864
	ds_read_b128 v[184:187], v174 offset:37888
	ds_read_b128 v[192:195], v174 offset:38912
	ds_read_b128 v[196:199], v174 offset:39936
	global_load_lds_dwordx4 v146, s[0:1]
	s_mov_b32 m0, s55
	s_nop 0
	global_load_lds_dwordx4 v150, s[0:1]
	s_waitcnt lgkmcnt(8)
	s_barrier
	s_waitcnt lgkmcnt(0)
	s_setprio 1
	s_waitcnt lgkmcnt(0)
	v_mfma_f32_16x16x32_bf16 v[126:129], v[130:133], v[158:161], v[126:129]
	v_mfma_f32_16x16x32_bf16 v[122:125], v[138:141], v[158:161], v[122:125]
	v_mfma_f32_16x16x32_bf16 v[118:121], v[130:133], v[166:169], v[118:121]
	v_mfma_f32_16x16x32_bf16 v[114:117], v[138:141], v[166:169], v[114:117]
	v_mfma_f32_16x16x32_bf16 v[110:113], v[130:133], v[180:183], v[110:113]
	v_mfma_f32_16x16x32_bf16 v[106:109], v[138:141], v[180:183], v[106:109]
	v_mfma_f32_16x16x32_bf16 v[102:105], v[130:133], v[192:195], v[102:105]
	v_mfma_f32_16x16x32_bf16 v[98:101], v[138:141], v[192:195], v[98:101]
	v_mfma_f32_16x16x32_bf16 v[126:129], v[134:137], v[162:165], v[126:129]
	v_mfma_f32_16x16x32_bf16 v[122:125], v[142:145], v[162:165], v[122:125]
	v_mfma_f32_16x16x32_bf16 v[118:121], v[134:137], v[176:179], v[118:121]
	v_mfma_f32_16x16x32_bf16 v[114:117], v[142:145], v[176:179], v[114:117]
	v_mfma_f32_16x16x32_bf16 v[110:113], v[134:137], v[184:187], v[110:113]
	v_mfma_f32_16x16x32_bf16 v[106:109], v[142:145], v[184:187], v[106:109]
	v_mfma_f32_16x16x32_bf16 v[102:105], v[134:137], v[196:199], v[102:105]
	v_mfma_f32_16x16x32_bf16 v[98:101], v[142:145], v[196:199], v[98:101]
	s_setprio 0
	s_barrier
	s_add_i32 s11, 0, 0x1c000
	s_add_i32 s0, s10, s51
	v_add_u32_e32 v175, s11, v172
	s_add_u32 s98, s46, 0x80
	s_addc_u32 s99, s47, 0
	s_mov_b32 m0, s0
	ds_read_b128 v[200:203], v175
	ds_read_b128 v[204:207], v175 offset:1024
	ds_read_b128 v[208:211], v175 offset:2048
	ds_read_b128 v[212:215], v175 offset:3072
	global_load_lds_dwordx4 v148, s[98:99]
	s_add_i32 m0, s0, 0x2000
	s_nop 0
	global_load_lds_dwordx4 v152, s[98:99]
	s_barrier
; #define G_STAGE(bufoff, gbase, voff) do { _Pragma("unroll") for (int _i = 0; _i < 2; ++_i) \
;         __builtin_amdgcn_global_load_lds((const unsigned*)((const char*)(gbase) + (voff)[_i]), (LAS unsigned*)(lds + (bufoff) + ldsw + _i * 8192), 16, 0, 0); } while (0)
; #define G_WAIT_V(n) asm volatile("s_waitcnt vmcnt(" #n ")" ::: "memory")
; #define G_WAIT_L(n) asm volatile("s_waitcnt lgkmcnt(" #n ")" ::: "memory")
; #define G_BAR __builtin_amdgcn_s_barrier()
; #define G_SCHED __builtin_amdgcn_sched_barrier(0)
; template <int MODE  , class Epi, class Sched>
; __device__ __forceinline__ void gemm_phase(LAS unsigned char* lds, const GemmDesc g, const Sched& S, const Epi& E) {
;     ...
;             G_LDB(B1, 1, 1); G_STAGE(G_SB(1, 0), b3, voffB);
;             G_BAR; G_WAIT_L(0); G_MMA(0, 1, At, B1); G_BAR;
;             G_LDA(At, 1, 1); G_STAGE(G_SA(1, 0), a3, voffA);
;             G_BAR; G_WAIT_L(0); G_MMA(1, 0, At, B0); G_BAR; G_SCHED;
;             G_STAGE(G_SB(1, 1), b3 + hstepB, voffB);
;             G_WAIT_V(6); G_BAR; G_MMA(1, 1, At, B1); G_BAR;
	s_waitcnt lgkmcnt(0)
	s_setprio 1
	s_waitcnt lgkmcnt(0)
	v_mfma_f32_16x16x32_bf16 v[94:97], v[200:203], v[158:161], v[94:97]
	v_mfma_f32_16x16x32_bf16 v[90:93], v[208:211], v[158:161], v[90:93]
	v_mfma_f32_16x16x32_bf16 v[86:89], v[200:203], v[166:169], v[86:89]
	v_mfma_f32_16x16x32_bf16 v[82:85], v[208:211], v[166:169], v[82:85]
	v_mfma_f32_16x16x32_bf16 v[78:81], v[200:203], v[180:183], v[78:81]
	v_mfma_f32_16x16x32_bf16 v[74:77], v[208:211], v[180:183], v[74:77]
	v_mfma_f32_16x16x32_bf16 v[70:73], v[200:203], v[192:195], v[70:73]
	v_mfma_f32_16x16x32_bf16 v[66:69], v[208:211], v[192:195], v[66:69]
	v_mfma_f32_16x16x32_bf16 v[94:97], v[204:207], v[162:165], v[94:97]
	v_mfma_f32_16x16x32_bf16 v[90:93], v[212:215], v[162:165], v[90:93]
	v_mfma_f32_16x16x32_bf16 v[86:89], v[204:207], v[176:179], v[86:89]
	v_mfma_f32_16x16x32_bf16 v[82:85], v[212:215], v[176:179], v[82:85]
	v_mfma_f32_16x16x32_bf16 v[78:81], v[204:207], v[184:187], v[78:81]
	v_mfma_f32_16x16x32_bf16 v[74:77], v[212:215], v[184:187], v[74:77]
	v_mfma_f32_16x16x32_bf16 v[70:73], v[204:207], v[196:199], v[70:73]
	v_mfma_f32_16x16x32_bf16 v[66:69], v[212:215], v[196:199], v[66:69]
	s_setprio 0
	s_mov_b32 m0, s56
	s_add_u32 s98, s48, 0x80
	s_addc_u32 s99, s49, 0
	s_barrier
	ds_read_b128 v[158:161], v174 offset:49152
	ds_read_b128 v[162:165], v174 offset:50176
	ds_read_b128 v[166:169], v174 offset:51200
	ds_read_b128 v[176:179], v174 offset:52224
	ds_read_b128 v[180:183], v174 offset:53248
	ds_read_b128 v[184:187], v174 offset:54272
	ds_read_b128 v[192:195], v174 offset:55296
	ds_read_b128 v[196:199], v174 offset:56320
	global_load_lds_dwordx4 v146, s[98:99]
	s_mov_b32 m0, s57
	s_nop 0
	global_load_lds_dwordx4 v150, s[98:99]
	s_barrier
	s_waitcnt lgkmcnt(0)
	s_setprio 1
	s_waitcnt lgkmcnt(0)
	v_mfma_f32_16x16x32_bf16 v[62:65], v[130:133], v[158:161], v[62:65]
	v_mfma_f32_16x16x32_bf16 v[58:61], v[138:141], v[158:161], v[58:61]
	v_mfma_f32_16x16x32_bf16 v[54:57], v[130:133], v[166:169], v[54:57]
	v_mfma_f32_16x16x32_bf16 v[50:53], v[138:141], v[166:169], v[50:53]
	v_mfma_f32_16x16x32_bf16 v[46:49], v[130:133], v[180:183], v[46:49]
	v_mfma_f32_16x16x32_bf16 v[42:45], v[138:141], v[180:183], v[42:45]
	v_mfma_f32_16x16x32_bf16 v[38:41], v[130:133], v[192:195], v[38:41]
	v_mfma_f32_16x16x32_bf16 v[34:37], v[138:141], v[192:195], v[34:37]
	v_mfma_f32_16x16x32_bf16 v[62:65], v[134:137], v[162:165], v[62:65]
	v_mfma_f32_16x16x32_bf16 v[58:61], v[142:145], v[162:165], v[58:61]
	v_mfma_f32_16x16x32_bf16 v[54:57], v[134:137], v[176:179], v[54:57]
	v_mfma_f32_16x16x32_bf16 v[50:53], v[142:145], v[176:179], v[50:53]
	v_mfma_f32_16x16x32_bf16 v[46:49], v[134:137], v[184:187], v[46:49]
	v_mfma_f32_16x16x32_bf16 v[42:45], v[142:145], v[184:187], v[42:45]
	v_mfma_f32_16x16x32_bf16 v[38:41], v[134:137], v[196:199], v[38:41]
	v_mfma_f32_16x16x32_bf16 v[34:37], v[142:145], v[196:199], v[34:37]
	s_setprio 0
	s_barrier
	s_add_u32 s0, s46, 0x84080
	s_addc_u32 s1, s47, 0
	s_add_i32 s10, s11, s51
	s_mov_b32 m0, s10
	s_nop 0
	global_load_lds_dwordx4 v148, s[0:1]
	s_add_i32 m0, s10, 0x2000
	s_nop 0
	global_load_lds_dwordx4 v152, s[0:1]
	s_waitcnt vmcnt(6)
	s_barrier
	s_setprio 1
	v_mfma_f32_16x16x32_bf16 v[30:33], v[200:203], v[158:161], v[30:33]
	s_add_i32 s68, s68, 2
	s_add_u32 s21, s21, 0x100
	s_addc_u32 s67, s67, 0
	s_cmp_gt_u32 s68, 13
	s_mov_b64 s[42:43], s[44:45]
	v_mfma_f32_16x16x32_bf16 v[26:29], v[208:211], v[158:161], v[26:29]
	v_mfma_f32_16x16x32_bf16 v[22:25], v[200:203], v[166:169], v[22:25]
	v_mfma_f32_16x16x32_bf16 v[18:21], v[208:211], v[166:169], v[18:21]
	v_mfma_f32_16x16x32_bf16 v[14:17], v[200:203], v[180:183], v[14:17]
	v_mfma_f32_16x16x32_bf16 v[10:13], v[208:211], v[180:183], v[10:13]
	v_mfma_f32_16x16x32_bf16 v[6:9], v[200:203], v[192:195], v[6:9]
	v_mfma_f32_16x16x32_bf16 v[2:5], v[208:211], v[192:195], v[2:5]
	v_mfma_f32_16x16x32_bf16 v[30:33], v[204:207], v[162:165], v[30:33]
	v_mfma_f32_16x16x32_bf16 v[26:29], v[212:215], v[162:165], v[26:29]
	v_mfma_f32_16x16x32_bf16 v[22:25], v[204:207], v[176:179], v[22:25]
	v_mfma_f32_16x16x32_bf16 v[18:21], v[212:215], v[176:179], v[18:21]
	v_mfma_f32_16x16x32_bf16 v[14:17], v[204:207], v[184:187], v[14:17]
	v_mfma_f32_16x16x32_bf16 v[10:13], v[212:215], v[184:187], v[10:13]
	v_mfma_f32_16x16x32_bf16 v[6:9], v[204:207], v[196:199], v[6:9]
	v_mfma_f32_16x16x32_bf16 v[2:5], v[212:215], v[196:199], v[2:5]
	s_setprio 0
	s_cbranch_scc1 .Lkdone_sa
	s_barrier
	s_branch .LBB0_815

; #define G_STAGE(bufoff, gbase, voff) do { _Pragma("unroll") for (int _i = 0; _i < 2; ++_i) \
;         __builtin_amdgcn_global_load_lds((const unsigned*)((const char*)(gbase) + (voff)[_i]), (LAS unsigned*)(lds + (bufoff) + ldsw + _i * 8192), 16, 0, 0); } while (0)
; #define G_WAIT_V(n) asm volatile("s_waitcnt vmcnt(" #n ")" ::: "memory")
; #define G_WAIT_L(n) asm volatile("s_waitcnt lgkmcnt(" #n ")" ::: "memory")
; #define G_BAR __builtin_amdgcn_s_barrier()
; #define G_SCHED __builtin_amdgcn_sched_barrier(0)
; template <int MODE  , class Epi, class Sched>
; __device__ __forceinline__ void gemm_phase(LAS unsigned char* lds, const GemmDesc g, const Sched& S, const Epi& E) {
;     ...
;             const bool last = (t == nt - 2);
;             const char* a1 = cA + (size_t)(t + 1) * kstep;
;             const char* a2 = last ? nA : cA + (size_t)(t + 2) * kstep; const char* b2 = last ? nB : cB + (size_t)(t + 2) * kstep;
;             const char* a3 = a2 + kstep; const char* b3 = b2 + kstep;
;             G_LDB(B0, 0, 0); G_SCHED; G_LDA(At, 0, 0); G_STAGE(G_SA(1, 1), a1 + hstepA, voffA);
;             G_WAIT_L(8); G_BAR; G_WAIT_L(0); G_MMA(0, 0, At, B0); G_BAR; G_SCHED;
;             G_LDB(B1, 0, 1); G_STAGE(G_SB(0, 0), b2, voffB);
;             G_BAR; G_WAIT_L(0); G_MMA(0, 1, At, B1); G_BAR;
;             G_LDA(At, 0, 1); G_STAGE(G_SA(0, 0), a2, voffA);
;             G_BAR; G_WAIT_L(0); G_MMA(1, 0, At, B0); G_BAR; G_SCHED;
;             G_STAGE(G_SB(0, 1), b2 + hstepB, voffB);
;             G_WAIT_V(6); G_BAR; G_MMA(1, 1, At, B1); G_BAR;
.Lnodb_sb:
.LBB0_897:
	v_add_u32_e32 v142, s57, v174
	ds_read_b128 v[130:133], v142
	ds_read_b128 v[134:137], v142 offset:1024
	ds_read_b128 v[138:141], v142 offset:2048
	ds_read_b128 v[142:145], v142 offset:3072
	s_add_u32 s42, s40, 0x100
	s_addc_u32 s43, s41, 0
	s_cmp_eq_u32 s71, 12
	s_cselect_b32 s47, s21, s43
	s_cselect_b32 s46, s20, s42
	s_cselect_b32 s45, s3, s70
	s_cselect_b32 s44, s2, s19
	s_add_u32 s98, s40, 0x84080
	s_addc_u32 s99, s41, 0
	s_add_i32 m0, s50, 0xc000
	ds_read_b128 v[158:161], v176
	ds_read_b128 v[162:165], v176 offset:1024
	ds_read_b128 v[166:169], v176 offset:2048
	ds_read_b128 v[170:173], v176 offset:3072
	ds_read_b128 v[178:181], v176 offset:4096
	ds_read_b128 v[182:185], v176 offset:5120
	ds_read_b128 v[186:189], v176 offset:6144
	ds_read_b128 v[192:195], v176 offset:7168
	global_load_lds_dwordx4 v146, s[98:99]
	s_add_i32 m0, s50, 0xe000
	s_nop 0
	global_load_lds_dwordx4 v150, s[98:99]
	s_waitcnt lgkmcnt(8)
	s_barrier
	s_waitcnt lgkmcnt(0)
	s_setprio 1
	s_waitcnt lgkmcnt(0)
	v_mfma_f32_16x16x32_bf16 v[126:129], v[130:133], v[158:161], v[126:129]
	v_mfma_f32_16x16x32_bf16 v[122:125], v[138:141], v[158:161], v[122:125]
	v_mfma_f32_16x16x32_bf16 v[118:121], v[130:133], v[166:169], v[118:121]
	v_mfma_f32_16x16x32_bf16 v[114:117], v[138:141], v[166:169], v[114:117]
	v_mfma_f32_16x16x32_bf16 v[110:113], v[130:133], v[178:181], v[110:113]
	v_mfma_f32_16x16x32_bf16 v[106:109], v[138:141], v[178:181], v[106:109]
	v_mfma_f32_16x16x32_bf16 v[102:105], v[130:133], v[186:189], v[102:105]
	v_mfma_f32_16x16x32_bf16 v[98:101], v[138:141], v[186:189], v[98:101]
	v_mfma_f32_16x16x32_bf16 v[126:129], v[134:137], v[162:165], v[126:129]
	v_mfma_f32_16x16x32_bf16 v[122:125], v[142:145], v[162:165], v[122:125]
	v_mfma_f32_16x16x32_bf16 v[118:121], v[134:137], v[170:173], v[118:121]
	v_mfma_f32_16x16x32_bf16 v[114:117], v[142:145], v[170:173], v[114:117]
	v_mfma_f32_16x16x32_bf16 v[110:113], v[134:137], v[182:185], v[110:113]
	v_mfma_f32_16x16x32_bf16 v[106:109], v[142:145], v[182:185], v[106:109]
	v_mfma_f32_16x16x32_bf16 v[102:105], v[134:137], v[192:195], v[102:105]
	v_mfma_f32_16x16x32_bf16 v[98:101], v[142:145], v[192:195], v[98:101]
	s_setprio 0
	s_barrier
	s_add_i32 s0, s57, s49
	v_add_u32_e32 v177, s58, v174
	s_mov_b32 m0, s0
	ds_read_b128 v[196:199], v177
	ds_read_b128 v[200:203], v177 offset:1024
	ds_read_b128 v[204:207], v177 offset:2048
	ds_read_b128 v[208:211], v177 offset:3072
	global_load_lds_dwordx4 v148, s[44:45]
	s_add_i32 m0, s0, 0x2000
	s_nop 0
	global_load_lds_dwordx4 v152, s[44:45]
	s_barrier
	s_waitcnt lgkmcnt(0)
	s_setprio 1
	s_waitcnt lgkmcnt(0)
	v_mfma_f32_16x16x32_bf16 v[94:97], v[196:199], v[158:161], v[94:97]
	v_mfma_f32_16x16x32_bf16 v[90:93], v[204:207], v[158:161], v[90:93]
	v_mfma_f32_16x16x32_bf16 v[86:89], v[196:199], v[166:169], v[86:89]
	v_mfma_f32_16x16x32_bf16 v[82:85], v[204:207], v[166:169], v[82:85]
	v_mfma_f32_16x16x32_bf16 v[78:81], v[196:199], v[178:181], v[78:81]
	v_mfma_f32_16x16x32_bf16 v[74:77], v[204:207], v[178:181], v[74:77]
	v_mfma_f32_16x16x32_bf16 v[70:73], v[196:199], v[186:189], v[70:73]
	v_mfma_f32_16x16x32_bf16 v[66:69], v[204:207], v[186:189], v[66:69]
	v_mfma_f32_16x16x32_bf16 v[94:97], v[200:203], v[162:165], v[94:97]
	v_mfma_f32_16x16x32_bf16 v[90:93], v[208:211], v[162:165], v[90:93]
	v_mfma_f32_16x16x32_bf16 v[86:89], v[200:203], v[170:173], v[86:89]
	v_mfma_f32_16x16x32_bf16 v[82:85], v[208:211], v[170:173], v[82:85]
	v_mfma_f32_16x16x32_bf16 v[78:81], v[200:203], v[182:185], v[78:81]
	v_mfma_f32_16x16x32_bf16 v[74:77], v[208:211], v[182:185], v[74:77]
	v_mfma_f32_16x16x32_bf16 v[70:73], v[200:203], v[192:195], v[70:73]
	v_mfma_f32_16x16x32_bf16 v[66:69], v[208:211], v[192:195], v[66:69]
	s_setprio 0
	s_mov_b32 m0, s50
	s_barrier
	ds_read_b128 v[158:161], v176 offset:16384
	ds_read_b128 v[162:165], v176 offset:17408
	ds_read_b128 v[166:169], v176 offset:18432
	ds_read_b128 v[170:173], v176 offset:19456
	ds_read_b128 v[178:181], v176 offset:20480
	ds_read_b128 v[182:185], v176 offset:21504
	ds_read_b128 v[186:189], v176 offset:22528
	ds_read_b128 v[192:195], v176 offset:23552
	global_load_lds_dwordx4 v146, s[46:47]
	s_mov_b32 m0, s51
	s_nop 0
	global_load_lds_dwordx4 v150, s[46:47]
	s_barrier
	s_waitcnt lgkmcnt(0)
	s_setprio 1
	s_waitcnt lgkmcnt(0)
	v_mfma_f32_16x16x32_bf16 v[62:65], v[130:133], v[158:161], v[62:65]
	v_mfma_f32_16x16x32_bf16 v[58:61], v[138:141], v[158:161], v[58:61]
	v_mfma_f32_16x16x32_bf16 v[54:57], v[130:133], v[166:169], v[54:57]
	v_mfma_f32_16x16x32_bf16 v[50:53], v[138:141], v[166:169], v[50:53]
	v_mfma_f32_16x16x32_bf16 v[46:49], v[130:133], v[178:181], v[46:49]
	v_mfma_f32_16x16x32_bf16 v[42:45], v[138:141], v[178:181], v[42:45]
	v_mfma_f32_16x16x32_bf16 v[38:41], v[130:133], v[186:189], v[38:41]
	v_mfma_f32_16x16x32_bf16 v[34:37], v[138:141], v[186:189], v[34:37]
	v_mfma_f32_16x16x32_bf16 v[62:65], v[134:137], v[162:165], v[62:65]
	v_mfma_f32_16x16x32_bf16 v[58:61], v[142:145], v[162:165], v[58:61]
	v_mfma_f32_16x16x32_bf16 v[54:57], v[134:137], v[170:173], v[54:57]
	v_mfma_f32_16x16x32_bf16 v[50:53], v[142:145], v[170:173], v[50:53]
	v_mfma_f32_16x16x32_bf16 v[46:49], v[134:137], v[182:185], v[46:49]
	v_mfma_f32_16x16x32_bf16 v[42:45], v[142:145], v[182:185], v[42:45]
	v_mfma_f32_16x16x32_bf16 v[38:41], v[134:137], v[192:195], v[38:41]
	v_mfma_f32_16x16x32_bf16 v[34:37], v[142:145], v[192:195], v[34:37]
	s_setprio 0
	s_barrier
	s_add_u32 s0, s44, 0x84000
	s_addc_u32 s1, s45, 0
	s_add_i32 s10, s58, s49
	s_mov_b32 m0, s10
	s_nop 0
	global_load_lds_dwordx4 v148, s[0:1]
	s_add_i32 m0, s10, 0x2000
	s_nop 0
	global_load_lds_dwordx4 v152, s[0:1]
	s_waitcnt vmcnt(6)
	s_barrier
; #define G_STAGE(bufoff, gbase, voff) do { _Pragma("unroll") for (int _i = 0; _i < 2; ++_i) \
;         __builtin_amdgcn_global_load_lds((const unsigned*)((const char*)(gbase) + (voff)[_i]), (LAS unsigned*)(lds + (bufoff) + ldsw + _i * 8192), 16, 0, 0); } while (0)
; #define G_WAIT_V(n) asm volatile("s_waitcnt vmcnt(" #n ")" ::: "memory")
; #define G_WAIT_L(n) asm volatile("s_waitcnt lgkmcnt(" #n ")" ::: "memory")
; #define G_BAR __builtin_amdgcn_s_barrier()
; #define G_SCHED __builtin_amdgcn_sched_barrier(0)
; template <int MODE  , class Epi, class Sched>
; __device__ __forceinline__ void gemm_phase(LAS unsigned char* lds, const GemmDesc g, const Sched& S, const Epi& E) {
;     ...
;             G_WAIT_V(6); G_BAR; G_MMA(1, 1, At, B1); G_BAR;
;             G_LDB(B0, 1, 0); G_SCHED; G_LDA(At, 1, 0); G_STAGE(G_SA(0, 1), a2 + hstepA, voffA);
;             G_WAIT_L(8); G_BAR; G_WAIT_L(0); G_MMA(0, 0, At, B0); G_BAR; G_SCHED;
;             G_LDB(B1, 1, 1); G_STAGE(G_SB(1, 0), b3, voffB);
;             G_BAR; G_WAIT_L(0); G_MMA(0, 1, At, B1); G_BAR;
	s_setprio 1
	v_mfma_f32_16x16x32_bf16 v[30:33], v[196:199], v[158:161], v[30:33]
	v_mfma_f32_16x16x32_bf16 v[26:29], v[204:207], v[158:161], v[26:29]
	v_mfma_f32_16x16x32_bf16 v[22:25], v[196:199], v[166:169], v[22:25]
	v_mfma_f32_16x16x32_bf16 v[18:21], v[204:207], v[166:169], v[18:21]
	v_mfma_f32_16x16x32_bf16 v[14:17], v[196:199], v[178:181], v[14:17]
	v_mfma_f32_16x16x32_bf16 v[10:13], v[204:207], v[178:181], v[10:13]
	v_mfma_f32_16x16x32_bf16 v[6:9], v[196:199], v[186:189], v[6:9]
	v_mfma_f32_16x16x32_bf16 v[2:5], v[204:207], v[186:189], v[2:5]
	v_mfma_f32_16x16x32_bf16 v[30:33], v[200:203], v[162:165], v[30:33]
	v_mfma_f32_16x16x32_bf16 v[26:29], v[208:211], v[162:165], v[26:29]
	v_mfma_f32_16x16x32_bf16 v[22:25], v[200:203], v[170:173], v[22:25]
	v_mfma_f32_16x16x32_bf16 v[18:21], v[208:211], v[170:173], v[18:21]
	v_mfma_f32_16x16x32_bf16 v[14:17], v[200:203], v[182:185], v[14:17]
	v_mfma_f32_16x16x32_bf16 v[10:13], v[208:211], v[182:185], v[10:13]
	v_mfma_f32_16x16x32_bf16 v[6:9], v[200:203], v[192:195], v[6:9]
	v_mfma_f32_16x16x32_bf16 v[2:5], v[208:211], v[192:195], v[2:5]
	s_setprio 0
	s_add_i32 s10, 0, 0x18000
	v_add_u32_e32 v142, s10, v174
	s_barrier
	ds_read_b128 v[130:133], v142
	ds_read_b128 v[134:137], v142 offset:1024
	ds_read_b128 v[138:141], v142 offset:2048
	ds_read_b128 v[142:145], v142 offset:3072
	s_add_u32 s0, s46, 0x84000
	s_addc_u32 s1, s47, 0
	s_mov_b32 m0, s52
	ds_read_b128 v[158:161], v176 offset:32768
	ds_read_b128 v[162:165], v176 offset:33792
	ds_read_b128 v[166:169], v176 offset:34816
	ds_read_b128 v[170:173], v176 offset:35840
	ds_read_b128 v[178:181], v176 offset:36864
	ds_read_b128 v[182:185], v176 offset:37888
	ds_read_b128 v[186:189], v176 offset:38912
	ds_read_b128 v[192:195], v176 offset:39936
	global_load_lds_dwordx4 v146, s[0:1]
	s_mov_b32 m0, s53
	s_nop 0
	global_load_lds_dwordx4 v150, s[0:1]
	s_waitcnt lgkmcnt(8)
	s_barrier
	s_waitcnt lgkmcnt(0)
	s_setprio 1
	s_waitcnt lgkmcnt(0)
	v_mfma_f32_16x16x32_bf16 v[126:129], v[130:133], v[158:161], v[126:129]
	v_mfma_f32_16x16x32_bf16 v[122:125], v[138:141], v[158:161], v[122:125]
	v_mfma_f32_16x16x32_bf16 v[118:121], v[130:133], v[166:169], v[118:121]
	v_mfma_f32_16x16x32_bf16 v[114:117], v[138:141], v[166:169], v[114:117]
	v_mfma_f32_16x16x32_bf16 v[110:113], v[130:133], v[178:181], v[110:113]
	v_mfma_f32_16x16x32_bf16 v[106:109], v[138:141], v[178:181], v[106:109]
	v_mfma_f32_16x16x32_bf16 v[102:105], v[130:133], v[186:189], v[102:105]
	v_mfma_f32_16x16x32_bf16 v[98:101], v[138:141], v[186:189], v[98:101]
	v_mfma_f32_16x16x32_bf16 v[126:129], v[134:137], v[162:165], v[126:129]
	v_mfma_f32_16x16x32_bf16 v[122:125], v[142:145], v[162:165], v[122:125]
	v_mfma_f32_16x16x32_bf16 v[118:121], v[134:137], v[170:173], v[118:121]
	v_mfma_f32_16x16x32_bf16 v[114:117], v[142:145], v[170:173], v[114:117]
	v_mfma_f32_16x16x32_bf16 v[110:113], v[134:137], v[182:185], v[110:113]
	v_mfma_f32_16x16x32_bf16 v[106:109], v[142:145], v[182:185], v[106:109]
	v_mfma_f32_16x16x32_bf16 v[102:105], v[134:137], v[192:195], v[102:105]
	v_mfma_f32_16x16x32_bf16 v[98:101], v[142:145], v[192:195], v[98:101]
	s_setprio 0
	s_barrier
	s_add_i32 s11, 0, 0x1c000
	s_add_i32 s0, s10, s49
	v_add_u32_e32 v177, s11, v174
	s_add_u32 s98, s44, 0x80
	s_addc_u32 s99, s45, 0
	s_mov_b32 m0, s0
	ds_read_b128 v[196:199], v177
	ds_read_b128 v[200:203], v177 offset:1024
	ds_read_b128 v[204:207], v177 offset:2048
	ds_read_b128 v[208:211], v177 offset:3072
	global_load_lds_dwordx4 v148, s[98:99]
	s_add_i32 m0, s0, 0x2000
	s_nop 0
	global_load_lds_dwordx4 v152, s[98:99]
	s_barrier
; #define G_STAGE(bufoff, gbase, voff) do { _Pragma("unroll") for (int _i = 0; _i < 2; ++_i) \
;         __builtin_amdgcn_global_load_lds((const unsigned*)((const char*)(gbase) + (voff)[_i]), (LAS unsigned*)(lds + (bufoff) + ldsw + _i * 8192), 16, 0, 0); } while (0)
; #define G_WAIT_V(n) asm volatile("s_waitcnt vmcnt(" #n ")" ::: "memory")
; #define G_WAIT_L(n) asm volatile("s_waitcnt lgkmcnt(" #n ")" ::: "memory")
; #define G_BAR __builtin_amdgcn_s_barrier()
; #define G_SCHED __builtin_amdgcn_sched_barrier(0)
; template <int MODE  , class Epi, class Sched>
; __device__ __forceinline__ void gemm_phase(LAS unsigned char* lds, const GemmDesc g, const Sched& S, const Epi& E) {
;     ...
;             G_LDB(B1, 1, 1); G_STAGE(G_SB(1, 0), b3, voffB);
;             G_BAR; G_WAIT_L(0); G_MMA(0, 1, At, B1); G_BAR;
;             G_LDA(At, 1, 1); G_STAGE(G_SA(1, 0), a3, voffA);
;             G_BAR; G_WAIT_L(0); G_MMA(1, 0, At, B0); G_BAR; G_SCHED;
;             G_STAGE(G_SB(1, 1), b3 + hstepB, voffB);
;             G_WAIT_V(6); G_BAR; G_MMA(1, 1, At, B1); G_BAR;
;         }
	s_waitcnt lgkmcnt(0)
	s_setprio 1
	s_waitcnt lgkmcnt(0)
	v_mfma_f32_16x16x32_bf16 v[94:97], v[196:199], v[158:161], v[94:97]
	v_mfma_f32_16x16x32_bf16 v[90:93], v[204:207], v[158:161], v[90:93]
	v_mfma_f32_16x16x32_bf16 v[86:89], v[196:199], v[166:169], v[86:89]
	v_mfma_f32_16x16x32_bf16 v[82:85], v[204:207], v[166:169], v[82:85]
	v_mfma_f32_16x16x32_bf16 v[78:81], v[196:199], v[178:181], v[78:81]
	v_mfma_f32_16x16x32_bf16 v[74:77], v[204:207], v[178:181], v[74:77]
	v_mfma_f32_16x16x32_bf16 v[70:73], v[196:199], v[186:189], v[70:73]
	v_mfma_f32_16x16x32_bf16 v[66:69], v[204:207], v[186:189], v[66:69]
	v_mfma_f32_16x16x32_bf16 v[94:97], v[200:203], v[162:165], v[94:97]
	v_mfma_f32_16x16x32_bf16 v[90:93], v[208:211], v[162:165], v[90:93]
	v_mfma_f32_16x16x32_bf16 v[86:89], v[200:203], v[170:173], v[86:89]
	v_mfma_f32_16x16x32_bf16 v[82:85], v[208:211], v[170:173], v[82:85]
	v_mfma_f32_16x16x32_bf16 v[78:81], v[200:203], v[182:185], v[78:81]
	v_mfma_f32_16x16x32_bf16 v[74:77], v[208:211], v[182:185], v[74:77]
	v_mfma_f32_16x16x32_bf16 v[70:73], v[200:203], v[192:195], v[70:73]
	v_mfma_f32_16x16x32_bf16 v[66:69], v[208:211], v[192:195], v[66:69]
	s_setprio 0
	s_mov_b32 m0, s54
	s_add_u32 s98, s46, 0x80
	s_addc_u32 s99, s47, 0
	s_barrier
	ds_read_b128 v[158:161], v176 offset:49152
	ds_read_b128 v[162:165], v176 offset:50176
	ds_read_b128 v[166:169], v176 offset:51200
	ds_read_b128 v[170:173], v176 offset:52224
	ds_read_b128 v[178:181], v176 offset:53248
	ds_read_b128 v[182:185], v176 offset:54272
	ds_read_b128 v[186:189], v176 offset:55296
	ds_read_b128 v[192:195], v176 offset:56320
	global_load_lds_dwordx4 v146, s[98:99]
	s_mov_b32 m0, s55
	s_nop 0
	global_load_lds_dwordx4 v150, s[98:99]
	s_barrier
	s_waitcnt lgkmcnt(0)
	s_setprio 1
	s_waitcnt lgkmcnt(0)
	v_mfma_f32_16x16x32_bf16 v[62:65], v[130:133], v[158:161], v[62:65]
	v_mfma_f32_16x16x32_bf16 v[58:61], v[138:141], v[158:161], v[58:61]
	v_mfma_f32_16x16x32_bf16 v[54:57], v[130:133], v[166:169], v[54:57]
	v_mfma_f32_16x16x32_bf16 v[50:53], v[138:141], v[166:169], v[50:53]
	v_mfma_f32_16x16x32_bf16 v[46:49], v[130:133], v[178:181], v[46:49]
	v_mfma_f32_16x16x32_bf16 v[42:45], v[138:141], v[178:181], v[42:45]
	v_mfma_f32_16x16x32_bf16 v[38:41], v[130:133], v[186:189], v[38:41]
	v_mfma_f32_16x16x32_bf16 v[34:37], v[138:141], v[186:189], v[34:37]
	v_mfma_f32_16x16x32_bf16 v[62:65], v[134:137], v[162:165], v[62:65]
	v_mfma_f32_16x16x32_bf16 v[58:61], v[142:145], v[162:165], v[58:61]
	v_mfma_f32_16x16x32_bf16 v[54:57], v[134:137], v[170:173], v[54:57]
	v_mfma_f32_16x16x32_bf16 v[50:53], v[142:145], v[170:173], v[50:53]
	v_mfma_f32_16x16x32_bf16 v[46:49], v[134:137], v[182:185], v[46:49]
	v_mfma_f32_16x16x32_bf16 v[42:45], v[142:145], v[182:185], v[42:45]
	v_mfma_f32_16x16x32_bf16 v[38:41], v[134:137], v[192:195], v[38:41]
	v_mfma_f32_16x16x32_bf16 v[34:37], v[142:145], v[192:195], v[34:37]
	s_setprio 0
	s_barrier
	s_add_u32 s0, s44, 0x84080
	s_addc_u32 s1, s45, 0
	s_add_i32 s10, s11, s49
	s_mov_b32 m0, s10
	s_nop 0
	global_load_lds_dwordx4 v148, s[0:1]
	s_add_i32 m0, s10, 0x2000
	s_nop 0
	global_load_lds_dwordx4 v152, s[0:1]
	s_waitcnt vmcnt(6)
	s_barrier
	s_setprio 1
	v_mfma_f32_16x16x32_bf16 v[30:33], v[196:199], v[158:161], v[30:33]
	s_add_i32 s71, s71, 2
	s_add_u32 s19, s19, 0x100
	s_addc_u32 s70, s70, 0
	s_cmp_gt_u32 s71, 13
	s_mov_b64 s[40:41], s[42:43]
	v_mfma_f32_16x16x32_bf16 v[26:29], v[204:207], v[158:161], v[26:29]
	v_mfma_f32_16x16x32_bf16 v[22:25], v[196:199], v[166:169], v[22:25]
	v_mfma_f32_16x16x32_bf16 v[18:21], v[204:207], v[166:169], v[18:21]
	v_mfma_f32_16x16x32_bf16 v[14:17], v[196:199], v[178:181], v[14:17]
	v_mfma_f32_16x16x32_bf16 v[10:13], v[204:207], v[178:181], v[10:13]
	v_mfma_f32_16x16x32_bf16 v[6:9], v[196:199], v[186:189], v[6:9]
	v_mfma_f32_16x16x32_bf16 v[2:5], v[204:207], v[186:189], v[2:5]
	v_mfma_f32_16x16x32_bf16 v[30:33], v[200:203], v[162:165], v[30:33]
	v_mfma_f32_16x16x32_bf16 v[26:29], v[208:211], v[162:165], v[26:29]
	v_mfma_f32_16x16x32_bf16 v[22:25], v[200:203], v[170:173], v[22:25]
	v_mfma_f32_16x16x32_bf16 v[18:21], v[208:211], v[170:173], v[18:21]
	v_mfma_f32_16x16x32_bf16 v[14:17], v[200:203], v[182:185], v[14:17]
	v_mfma_f32_16x16x32_bf16 v[10:13], v[208:211], v[182:185], v[10:13]
	v_mfma_f32_16x16x32_bf16 v[6:9], v[200:203], v[192:195], v[6:9]
	v_mfma_f32_16x16x32_bf16 v[2:5], v[208:211], v[192:195], v[2:5]
	s_setprio 0
	s_cbranch_scc1 .Lkdone_sb
	s_barrier
	s_branch .LBB0_897

; #define G_STAGE(bufoff, gbase, voff) do { _Pragma("unroll") for (int _i = 0; _i < 2; ++_i) \
;         __builtin_amdgcn_global_load_lds((const unsigned*)((const char*)(gbase) + (voff)[_i]), (LAS unsigned*)(lds + (bufoff) + ldsw + _i * 8192), 16, 0, 0); } while (0)
; #define G_WAIT_V(n) asm volatile("s_waitcnt vmcnt(" #n ")" ::: "memory")
; #define G_WAIT_L(n) asm volatile("s_waitcnt lgkmcnt(" #n ")" ::: "memory")
; #define G_BAR __builtin_amdgcn_s_barrier()
; #define G_SCHED __builtin_amdgcn_sched_barrier(0)
; template <int MODE  , class Epi, class Sched>
; __device__ __forceinline__ void gemm_phase(LAS unsigned char* lds, const GemmDesc g, const Sched& S, const Epi& E) {
;     ...
;             const bool last = (t == nt - 2);
;             const char* a1 = cA + (size_t)(t + 1) * kstep;
;             const char* a2 = last ? nA : cA + (size_t)(t + 2) * kstep; const char* b2 = last ? nB : cB + (size_t)(t + 2) * kstep;
;             const char* a3 = a2 + kstep; const char* b3 = b2 + kstep;
;             G_LDB(B0, 0, 0); G_SCHED; G_LDA(At, 0, 0); G_STAGE(G_SA(1, 1), a1 + hstepA, voffA);
;             G_WAIT_L(8); G_BAR; G_WAIT_L(0); G_MMA(0, 0, At, B0); G_BAR; G_SCHED;
;             G_LDB(B1, 0, 1); G_STAGE(G_SB(0, 0), b2, voffB);
;             G_BAR; G_WAIT_L(0); G_MMA(0, 1, At, B1); G_BAR;
;             G_LDA(At, 0, 1); G_STAGE(G_SA(0, 0), a2, voffA);
;             G_BAR; G_WAIT_L(0); G_MMA(1, 0, At, B0); G_BAR; G_SCHED;
;             G_STAGE(G_SB(0, 1), b2 + hstepB, voffB);
;             G_WAIT_V(6); G_BAR; G_MMA(1, 1, At, B1); G_BAR;
.Lnodb_sc:
.LBB0_987:
	v_add_u32_e32 v145, s50, v142
	ds_read_b128 v[146:149], v145
	ds_read_b128 v[150:153], v145 offset:1024
	ds_read_b128 v[154:157], v145 offset:2048
	ds_read_b128 v[158:161], v145 offset:3072
	s_add_u32 s34, s20, 0x100
	s_addc_u32 s35, s21, 0
	s_cmp_eq_u32 s60, 12
	s_cselect_b32 s43, s17, s35
	s_cselect_b32 s42, s16, s34
	s_cselect_b32 s41, s3, s59
	s_cselect_b32 s40, s2, s15
	s_add_u32 s98, s20, 0x84080
	s_addc_u32 s99, s21, 0
	s_add_i32 m0, s44, 0xc000
	ds_read_b128 v[162:165], v144
	ds_read_b128 v[166:169], v144 offset:1024
	ds_read_b128 v[170:173], v144 offset:2048
	ds_read_b128 v[174:177], v144 offset:3072
	ds_read_b128 v[178:181], v144 offset:4096
	ds_read_b128 v[182:185], v144 offset:5120
	ds_read_b128 v[186:189], v144 offset:6144
	ds_read_b128 v[192:195], v144 offset:7168
	global_load_lds_dwordx4 v130, s[98:99]
	s_add_i32 m0, s44, 0xe000
	s_nop 0
	global_load_lds_dwordx4 v134, s[98:99]
	s_waitcnt lgkmcnt(8)
	s_barrier
	s_waitcnt lgkmcnt(0)
	s_setprio 1
	s_waitcnt lgkmcnt(0)
	v_mfma_f32_16x16x32_bf16 v[126:129], v[146:149], v[162:165], v[126:129]
	v_mfma_f32_16x16x32_bf16 v[122:125], v[154:157], v[162:165], v[122:125]
	v_mfma_f32_16x16x32_bf16 v[118:121], v[146:149], v[170:173], v[118:121]
	v_mfma_f32_16x16x32_bf16 v[114:117], v[154:157], v[170:173], v[114:117]
	v_mfma_f32_16x16x32_bf16 v[110:113], v[146:149], v[178:181], v[110:113]
	v_mfma_f32_16x16x32_bf16 v[106:109], v[154:157], v[178:181], v[106:109]
	v_mfma_f32_16x16x32_bf16 v[102:105], v[146:149], v[186:189], v[102:105]
	v_mfma_f32_16x16x32_bf16 v[98:101], v[154:157], v[186:189], v[98:101]
	v_mfma_f32_16x16x32_bf16 v[126:129], v[150:153], v[166:169], v[126:129]
	v_mfma_f32_16x16x32_bf16 v[122:125], v[158:161], v[166:169], v[122:125]
	v_mfma_f32_16x16x32_bf16 v[118:121], v[150:153], v[174:177], v[118:121]
	v_mfma_f32_16x16x32_bf16 v[114:117], v[158:161], v[174:177], v[114:117]
	v_mfma_f32_16x16x32_bf16 v[110:113], v[150:153], v[182:185], v[110:113]
	v_mfma_f32_16x16x32_bf16 v[106:109], v[158:161], v[182:185], v[106:109]
	v_mfma_f32_16x16x32_bf16 v[102:105], v[150:153], v[192:195], v[102:105]
	v_mfma_f32_16x16x32_bf16 v[98:101], v[158:161], v[192:195], v[98:101]
	s_setprio 0
	s_barrier
	s_add_i32 s0, s50, s31
	v_add_u32_e32 v145, s51, v142
	s_mov_b32 m0, s0
	ds_read_b128 v[196:199], v145
	ds_read_b128 v[200:203], v145 offset:1024
	ds_read_b128 v[204:207], v145 offset:2048
	ds_read_b128 v[208:211], v145 offset:3072
	global_load_lds_dwordx4 v132, s[40:41]
	s_add_i32 m0, s0, 0x2000
	s_nop 0
	global_load_lds_dwordx4 v136, s[40:41]
	s_barrier
	s_waitcnt lgkmcnt(0)
	s_setprio 1
	s_waitcnt lgkmcnt(0)
	v_mfma_f32_16x16x32_bf16 v[94:97], v[196:199], v[162:165], v[94:97]
	v_mfma_f32_16x16x32_bf16 v[90:93], v[204:207], v[162:165], v[90:93]
	v_mfma_f32_16x16x32_bf16 v[86:89], v[196:199], v[170:173], v[86:89]
	v_mfma_f32_16x16x32_bf16 v[82:85], v[204:207], v[170:173], v[82:85]
	v_mfma_f32_16x16x32_bf16 v[78:81], v[196:199], v[178:181], v[78:81]
	v_mfma_f32_16x16x32_bf16 v[74:77], v[204:207], v[178:181], v[74:77]
	v_mfma_f32_16x16x32_bf16 v[70:73], v[196:199], v[186:189], v[70:73]
	v_mfma_f32_16x16x32_bf16 v[66:69], v[204:207], v[186:189], v[66:69]
	v_mfma_f32_16x16x32_bf16 v[94:97], v[200:203], v[166:169], v[94:97]
	v_mfma_f32_16x16x32_bf16 v[90:93], v[208:211], v[166:169], v[90:93]
	v_mfma_f32_16x16x32_bf16 v[86:89], v[200:203], v[174:177], v[86:89]
	v_mfma_f32_16x16x32_bf16 v[82:85], v[208:211], v[174:177], v[82:85]
	v_mfma_f32_16x16x32_bf16 v[78:81], v[200:203], v[182:185], v[78:81]
	v_mfma_f32_16x16x32_bf16 v[74:77], v[208:211], v[182:185], v[74:77]
	v_mfma_f32_16x16x32_bf16 v[70:73], v[200:203], v[192:195], v[70:73]
	v_mfma_f32_16x16x32_bf16 v[66:69], v[208:211], v[192:195], v[66:69]
	s_setprio 0
	s_mov_b32 m0, s44
	s_barrier
	ds_read_b128 v[162:165], v144 offset:16384
	ds_read_b128 v[166:169], v144 offset:17408
	ds_read_b128 v[170:173], v144 offset:18432
	ds_read_b128 v[174:177], v144 offset:19456
	ds_read_b128 v[178:181], v144 offset:20480
	ds_read_b128 v[182:185], v144 offset:21504
	ds_read_b128 v[186:189], v144 offset:22528
	ds_read_b128 v[192:195], v144 offset:23552
	global_load_lds_dwordx4 v130, s[42:43]
	s_mov_b32 m0, s45
	s_nop 0
	global_load_lds_dwordx4 v134, s[42:43]
	s_barrier
	s_waitcnt lgkmcnt(0)
	s_setprio 1
	s_waitcnt lgkmcnt(0)
	v_mfma_f32_16x16x32_bf16 v[62:65], v[146:149], v[162:165], v[62:65]
	v_mfma_f32_16x16x32_bf16 v[58:61], v[154:157], v[162:165], v[58:61]
	v_mfma_f32_16x16x32_bf16 v[54:57], v[146:149], v[170:173], v[54:57]
	v_mfma_f32_16x16x32_bf16 v[50:53], v[154:157], v[170:173], v[50:53]
	v_mfma_f32_16x16x32_bf16 v[46:49], v[146:149], v[178:181], v[46:49]
	v_mfma_f32_16x16x32_bf16 v[42:45], v[154:157], v[178:181], v[42:45]
	v_mfma_f32_16x16x32_bf16 v[38:41], v[146:149], v[186:189], v[38:41]
	v_mfma_f32_16x16x32_bf16 v[34:37], v[154:157], v[186:189], v[34:37]
	v_mfma_f32_16x16x32_bf16 v[62:65], v[150:153], v[166:169], v[62:65]
	v_mfma_f32_16x16x32_bf16 v[58:61], v[158:161], v[166:169], v[58:61]
	v_mfma_f32_16x16x32_bf16 v[54:57], v[150:153], v[174:177], v[54:57]
	v_mfma_f32_16x16x32_bf16 v[50:53], v[158:161], v[174:177], v[50:53]
	v_mfma_f32_16x16x32_bf16 v[46:49], v[150:153], v[182:185], v[46:49]
	v_mfma_f32_16x16x32_bf16 v[42:45], v[158:161], v[182:185], v[42:45]
	v_mfma_f32_16x16x32_bf16 v[38:41], v[150:153], v[192:195], v[38:41]
	v_mfma_f32_16x16x32_bf16 v[34:37], v[158:161], v[192:195], v[34:37]
	s_setprio 0
	s_barrier
	s_add_u32 s0, s40, 0x84000
	s_addc_u32 s1, s41, 0
	s_add_i32 s10, s51, s31
	s_mov_b32 m0, s10
	s_nop 0
	global_load_lds_dwordx4 v132, s[0:1]
	s_add_i32 m0, s10, 0x2000
	s_nop 0
	global_load_lds_dwordx4 v136, s[0:1]
	s_waitcnt vmcnt(6)
	s_barrier
; #define G_STAGE(bufoff, gbase, voff) do { _Pragma("unroll") for (int _i = 0; _i < 2; ++_i) \
;         __builtin_amdgcn_global_load_lds((const unsigned*)((const char*)(gbase) + (voff)[_i]), (LAS unsigned*)(lds + (bufoff) + ldsw + _i * 8192), 16, 0, 0); } while (0)
; #define G_WAIT_V(n) asm volatile("s_waitcnt vmcnt(" #n ")" ::: "memory")
; #define G_WAIT_L(n) asm volatile("s_waitcnt lgkmcnt(" #n ")" ::: "memory")
; #define G_BAR __builtin_amdgcn_s_barrier()
; #define G_SCHED __builtin_amdgcn_sched_barrier(0)
; template <int MODE  , class Epi, class Sched>
; __device__ __forceinline__ void gemm_phase(LAS unsigned char* lds, const GemmDesc g, const Sched& S, const Epi& E) {
;     ...
;             G_WAIT_V(6); G_BAR; G_MMA(1, 1, At, B1); G_BAR;
;             G_LDB(B0, 1, 0); G_SCHED; G_LDA(At, 1, 0); G_STAGE(G_SA(0, 1), a2 + hstepA, voffA);
;             G_WAIT_L(8); G_BAR; G_WAIT_L(0); G_MMA(0, 0, At, B0); G_BAR; G_SCHED;
;             G_LDB(B1, 1, 1); G_STAGE(G_SB(1, 0), b3, voffB);
;             G_BAR; G_WAIT_L(0); G_MMA(0, 1, At, B1); G_BAR;
	s_setprio 1
	v_mfma_f32_16x16x32_bf16 v[30:33], v[196:199], v[162:165], v[30:33]
	v_mfma_f32_16x16x32_bf16 v[26:29], v[204:207], v[162:165], v[26:29]
	v_mfma_f32_16x16x32_bf16 v[22:25], v[196:199], v[170:173], v[22:25]
	v_mfma_f32_16x16x32_bf16 v[18:21], v[204:207], v[170:173], v[18:21]
	v_mfma_f32_16x16x32_bf16 v[14:17], v[196:199], v[178:181], v[14:17]
	v_mfma_f32_16x16x32_bf16 v[10:13], v[204:207], v[178:181], v[10:13]
	v_mfma_f32_16x16x32_bf16 v[6:9], v[196:199], v[186:189], v[6:9]
	v_mfma_f32_16x16x32_bf16 v[2:5], v[204:207], v[186:189], v[2:5]
	v_mfma_f32_16x16x32_bf16 v[30:33], v[200:203], v[166:169], v[30:33]
	v_mfma_f32_16x16x32_bf16 v[26:29], v[208:211], v[166:169], v[26:29]
	v_mfma_f32_16x16x32_bf16 v[22:25], v[200:203], v[174:177], v[22:25]
	v_mfma_f32_16x16x32_bf16 v[18:21], v[208:211], v[174:177], v[18:21]
	v_mfma_f32_16x16x32_bf16 v[14:17], v[200:203], v[182:185], v[14:17]
	v_mfma_f32_16x16x32_bf16 v[10:13], v[208:211], v[182:185], v[10:13]
	v_mfma_f32_16x16x32_bf16 v[6:9], v[200:203], v[192:195], v[6:9]
	v_mfma_f32_16x16x32_bf16 v[2:5], v[208:211], v[192:195], v[2:5]
	s_setprio 0
	s_add_i32 s10, 0, 0x18000
	v_add_u32_e32 v145, s10, v142
	s_barrier
	ds_read_b128 v[146:149], v145
	ds_read_b128 v[150:153], v145 offset:1024
	ds_read_b128 v[154:157], v145 offset:2048
	ds_read_b128 v[158:161], v145 offset:3072
	s_add_u32 s0, s42, 0x84000
	s_addc_u32 s1, s43, 0
	s_mov_b32 m0, s46
	ds_read_b128 v[162:165], v144 offset:32768
	ds_read_b128 v[166:169], v144 offset:33792
	ds_read_b128 v[170:173], v144 offset:34816
	ds_read_b128 v[174:177], v144 offset:35840
	ds_read_b128 v[178:181], v144 offset:36864
	ds_read_b128 v[182:185], v144 offset:37888
	ds_read_b128 v[186:189], v144 offset:38912
	ds_read_b128 v[192:195], v144 offset:39936
	global_load_lds_dwordx4 v130, s[0:1]
	s_mov_b32 m0, s47
	s_nop 0
	global_load_lds_dwordx4 v134, s[0:1]
	s_waitcnt lgkmcnt(8)
	s_barrier
	s_waitcnt lgkmcnt(0)
	s_setprio 1
	s_waitcnt lgkmcnt(0)
	v_mfma_f32_16x16x32_bf16 v[126:129], v[146:149], v[162:165], v[126:129]
	v_mfma_f32_16x16x32_bf16 v[122:125], v[154:157], v[162:165], v[122:125]
	v_mfma_f32_16x16x32_bf16 v[118:121], v[146:149], v[170:173], v[118:121]
	v_mfma_f32_16x16x32_bf16 v[114:117], v[154:157], v[170:173], v[114:117]
	v_mfma_f32_16x16x32_bf16 v[110:113], v[146:149], v[178:181], v[110:113]
	v_mfma_f32_16x16x32_bf16 v[106:109], v[154:157], v[178:181], v[106:109]
	v_mfma_f32_16x16x32_bf16 v[102:105], v[146:149], v[186:189], v[102:105]
	v_mfma_f32_16x16x32_bf16 v[98:101], v[154:157], v[186:189], v[98:101]
	v_mfma_f32_16x16x32_bf16 v[126:129], v[150:153], v[166:169], v[126:129]
	v_mfma_f32_16x16x32_bf16 v[122:125], v[158:161], v[166:169], v[122:125]
	v_mfma_f32_16x16x32_bf16 v[118:121], v[150:153], v[174:177], v[118:121]
	v_mfma_f32_16x16x32_bf16 v[114:117], v[158:161], v[174:177], v[114:117]
	v_mfma_f32_16x16x32_bf16 v[110:113], v[150:153], v[182:185], v[110:113]
	v_mfma_f32_16x16x32_bf16 v[106:109], v[158:161], v[182:185], v[106:109]
	v_mfma_f32_16x16x32_bf16 v[102:105], v[150:153], v[192:195], v[102:105]
	v_mfma_f32_16x16x32_bf16 v[98:101], v[158:161], v[192:195], v[98:101]
	s_setprio 0
	s_barrier
	s_add_i32 s11, 0, 0x1c000
	s_add_i32 s0, s10, s31
	v_add_u32_e32 v145, s11, v142
	s_add_u32 s98, s40, 0x80
	s_addc_u32 s99, s41, 0
	s_mov_b32 m0, s0
	ds_read_b128 v[196:199], v145
	ds_read_b128 v[200:203], v145 offset:1024
	ds_read_b128 v[204:207], v145 offset:2048
	ds_read_b128 v[208:211], v145 offset:3072
	global_load_lds_dwordx4 v132, s[98:99]
	s_add_i32 m0, s0, 0x2000
	s_nop 0
	global_load_lds_dwordx4 v136, s[98:99]
	s_barrier
; #define G_STAGE(bufoff, gbase, voff) do { _Pragma("unroll") for (int _i = 0; _i < 2; ++_i) \
;         __builtin_amdgcn_global_load_lds((const unsigned*)((const char*)(gbase) + (voff)[_i]), (LAS unsigned*)(lds + (bufoff) + ldsw + _i * 8192), 16, 0, 0); } while (0)
; #define G_WAIT_V(n) asm volatile("s_waitcnt vmcnt(" #n ")" ::: "memory")
; #define G_WAIT_L(n) asm volatile("s_waitcnt lgkmcnt(" #n ")" ::: "memory")
; #define G_BAR __builtin_amdgcn_s_barrier()
; #define G_SCHED __builtin_amdgcn_sched_barrier(0)
; template <int MODE  , class Epi, class Sched>
; __device__ __forceinline__ void gemm_phase(LAS unsigned char* lds, const GemmDesc g, const Sched& S, const Epi& E) {
;     ...
;             G_LDB(B1, 1, 1); G_STAGE(G_SB(1, 0), b3, voffB);
;             G_BAR; G_WAIT_L(0); G_MMA(0, 1, At, B1); G_BAR;
;             G_LDA(At, 1, 1); G_STAGE(G_SA(1, 0), a3, voffA);
;             G_BAR; G_WAIT_L(0); G_MMA(1, 0, At, B0); G_BAR; G_SCHED;
;             G_STAGE(G_SB(1, 1), b3 + hstepB, voffB);
;             G_WAIT_V(6); G_BAR; G_MMA(1, 1, At, B1); G_BAR;
;         }
	s_waitcnt lgkmcnt(0)
	s_setprio 1
	s_waitcnt lgkmcnt(0)
	v_mfma_f32_16x16x32_bf16 v[94:97], v[196:199], v[162:165], v[94:97]
	v_mfma_f32_16x16x32_bf16 v[90:93], v[204:207], v[162:165], v[90:93]
	v_mfma_f32_16x16x32_bf16 v[86:89], v[196:199], v[170:173], v[86:89]
	v_mfma_f32_16x16x32_bf16 v[82:85], v[204:207], v[170:173], v[82:85]
	v_mfma_f32_16x16x32_bf16 v[78:81], v[196:199], v[178:181], v[78:81]
	v_mfma_f32_16x16x32_bf16 v[74:77], v[204:207], v[178:181], v[74:77]
	v_mfma_f32_16x16x32_bf16 v[70:73], v[196:199], v[186:189], v[70:73]
	v_mfma_f32_16x16x32_bf16 v[66:69], v[204:207], v[186:189], v[66:69]
	v_mfma_f32_16x16x32_bf16 v[94:97], v[200:203], v[166:169], v[94:97]
	v_mfma_f32_16x16x32_bf16 v[90:93], v[208:211], v[166:169], v[90:93]
	v_mfma_f32_16x16x32_bf16 v[86:89], v[200:203], v[174:177], v[86:89]
	v_mfma_f32_16x16x32_bf16 v[82:85], v[208:211], v[174:177], v[82:85]
	v_mfma_f32_16x16x32_bf16 v[78:81], v[200:203], v[182:185], v[78:81]
	v_mfma_f32_16x16x32_bf16 v[74:77], v[208:211], v[182:185], v[74:77]
	v_mfma_f32_16x16x32_bf16 v[70:73], v[200:203], v[192:195], v[70:73]
	v_mfma_f32_16x16x32_bf16 v[66:69], v[208:211], v[192:195], v[66:69]
	s_setprio 0
	s_mov_b32 m0, s48
	s_add_u32 s98, s42, 0x80
	s_addc_u32 s99, s43, 0
	s_barrier
	ds_read_b128 v[162:165], v144 offset:49152
	ds_read_b128 v[166:169], v144 offset:50176
	ds_read_b128 v[170:173], v144 offset:51200
	ds_read_b128 v[174:177], v144 offset:52224
	ds_read_b128 v[178:181], v144 offset:53248
	ds_read_b128 v[182:185], v144 offset:54272
	ds_read_b128 v[186:189], v144 offset:55296
	ds_read_b128 v[192:195], v144 offset:56320
	global_load_lds_dwordx4 v130, s[98:99]
	s_mov_b32 m0, s49
	s_nop 0
	global_load_lds_dwordx4 v134, s[98:99]
	s_barrier
	s_waitcnt lgkmcnt(0)
	s_setprio 1
	s_waitcnt lgkmcnt(0)
	v_mfma_f32_16x16x32_bf16 v[62:65], v[146:149], v[162:165], v[62:65]
	v_mfma_f32_16x16x32_bf16 v[58:61], v[154:157], v[162:165], v[58:61]
	v_mfma_f32_16x16x32_bf16 v[54:57], v[146:149], v[170:173], v[54:57]
	v_mfma_f32_16x16x32_bf16 v[50:53], v[154:157], v[170:173], v[50:53]
	v_mfma_f32_16x16x32_bf16 v[46:49], v[146:149], v[178:181], v[46:49]
	v_mfma_f32_16x16x32_bf16 v[42:45], v[154:157], v[178:181], v[42:45]
	v_mfma_f32_16x16x32_bf16 v[38:41], v[146:149], v[186:189], v[38:41]
	v_mfma_f32_16x16x32_bf16 v[34:37], v[154:157], v[186:189], v[34:37]
	v_mfma_f32_16x16x32_bf16 v[62:65], v[150:153], v[166:169], v[62:65]
	v_mfma_f32_16x16x32_bf16 v[58:61], v[158:161], v[166:169], v[58:61]
	v_mfma_f32_16x16x32_bf16 v[54:57], v[150:153], v[174:177], v[54:57]
	v_mfma_f32_16x16x32_bf16 v[50:53], v[158:161], v[174:177], v[50:53]
	v_mfma_f32_16x16x32_bf16 v[46:49], v[150:153], v[182:185], v[46:49]
	v_mfma_f32_16x16x32_bf16 v[42:45], v[158:161], v[182:185], v[42:45]
	v_mfma_f32_16x16x32_bf16 v[38:41], v[150:153], v[192:195], v[38:41]
	v_mfma_f32_16x16x32_bf16 v[34:37], v[158:161], v[192:195], v[34:37]
	s_setprio 0
	s_barrier
	s_add_u32 s0, s40, 0x84080
	s_addc_u32 s1, s41, 0
	s_add_i32 s10, s11, s31
	s_mov_b32 m0, s10
	s_nop 0
	global_load_lds_dwordx4 v132, s[0:1]
	s_add_i32 m0, s10, 0x2000
	s_nop 0
	global_load_lds_dwordx4 v136, s[0:1]
	s_waitcnt vmcnt(6)
	s_barrier
	s_setprio 1
	v_mfma_f32_16x16x32_bf16 v[30:33], v[196:199], v[162:165], v[30:33]
	s_add_i32 s60, s60, 2
	s_add_u32 s15, s15, 0x100
	s_addc_u32 s59, s59, 0
	s_cmp_gt_u32 s60, 13
	s_mov_b64 s[20:21], s[34:35]
	v_mfma_f32_16x16x32_bf16 v[26:29], v[204:207], v[162:165], v[26:29]
	v_mfma_f32_16x16x32_bf16 v[22:25], v[196:199], v[170:173], v[22:25]
	v_mfma_f32_16x16x32_bf16 v[18:21], v[204:207], v[170:173], v[18:21]
	v_mfma_f32_16x16x32_bf16 v[14:17], v[196:199], v[178:181], v[14:17]
	v_mfma_f32_16x16x32_bf16 v[10:13], v[204:207], v[178:181], v[10:13]
	v_mfma_f32_16x16x32_bf16 v[6:9], v[196:199], v[186:189], v[6:9]
	v_mfma_f32_16x16x32_bf16 v[2:5], v[204:207], v[186:189], v[2:5]
	v_mfma_f32_16x16x32_bf16 v[30:33], v[200:203], v[166:169], v[30:33]
	v_mfma_f32_16x16x32_bf16 v[26:29], v[208:211], v[166:169], v[26:29]
	v_mfma_f32_16x16x32_bf16 v[22:25], v[200:203], v[174:177], v[22:25]
	v_mfma_f32_16x16x32_bf16 v[18:21], v[208:211], v[174:177], v[18:21]
	v_mfma_f32_16x16x32_bf16 v[14:17], v[200:203], v[182:185], v[14:17]
	v_mfma_f32_16x16x32_bf16 v[10:13], v[208:211], v[182:185], v[10:13]
	v_mfma_f32_16x16x32_bf16 v[6:9], v[200:203], v[192:195], v[6:9]
	v_mfma_f32_16x16x32_bf16 v[2:5], v[208:211], v[192:195], v[2:5]
	s_setprio 0
	s_cbranch_scc1 .Lkdone_sc
	s_barrier
	s_branch .LBB0_987

; #define G_STAGE(bufoff, gbase, voff) do { _Pragma("unroll") for (int _i = 0; _i < 2; ++_i) \
;         __builtin_amdgcn_global_load_lds((const unsigned*)((const char*)(gbase) + (voff)[_i]), (LAS unsigned*)(lds + (bufoff) + ldsw + _i * 8192), 16, 0, 0); } while (0)
; #define G_WAIT_V(n) asm volatile("s_waitcnt vmcnt(" #n ")" ::: "memory")
; #define G_WAIT_L(n) asm volatile("s_waitcnt lgkmcnt(" #n ")" ::: "memory")
; #define G_BAR __builtin_amdgcn_s_barrier()
; #define G_SCHED __builtin_amdgcn_sched_barrier(0)
; template <int MODE  , class Epi, class Sched>
; __device__ __forceinline__ void gemm_phase(LAS unsigned char* lds, const GemmDesc g, const Sched& S, const Epi& E) {
;     ...
;             const bool last = (t == nt - 2);
;             const char* a1 = cA + (size_t)(t + 1) * kstep;
;             const char* a2 = last ? nA : cA + (size_t)(t + 2) * kstep; const char* b2 = last ? nB : cB + (size_t)(t + 2) * kstep;
;             const char* a3 = a2 + kstep; const char* b3 = b2 + kstep;
;             G_LDB(B0, 0, 0); G_SCHED; G_LDA(At, 0, 0); G_STAGE(G_SA(1, 1), a1 + hstepA, voffA);
;             G_WAIT_L(8); G_BAR; G_WAIT_L(0); G_MMA(0, 0, At, B0); G_BAR; G_SCHED;
;             G_LDB(B1, 0, 1); G_STAGE(G_SB(0, 0), b2, voffB);
;             G_BAR; G_WAIT_L(0); G_MMA(0, 1, At, B1); G_BAR;
;             G_LDA(At, 0, 1); G_STAGE(G_SA(0, 0), a2, voffA);
;             G_BAR; G_WAIT_L(0); G_MMA(1, 0, At, B0); G_BAR; G_SCHED;
;             G_STAGE(G_SB(0, 1), b2 + hstepB, voffB);
;             G_WAIT_V(6); G_BAR; G_MMA(1, 1, At, B1); G_BAR;
.Lnodb_s1a:
.LBB0_1017:
	ds_read_b128 v[130:133], v163
	ds_read_b128 v[134:137], v163 offset:1024
	ds_read_b128 v[154:157], v163 offset:2048
	ds_read_b128 v[170:173], v163 offset:3072
	s_add_u32 s4, s2, 0x100
	s_addc_u32 s5, s3, 0
	s_cmp_eq_u32 s87, 28
	s_cselect_b32 s53, s47, s5
	s_cselect_b32 s52, s46, s4
	s_cselect_b32 s51, s49, s86
	s_cselect_b32 s50, s48, s85
	s_add_u32 s98, s2, 0x84080
	s_addc_u32 s99, s3, 0
	s_add_i32 m0, s58, 0xc000
	ds_read_b128 v[174:177], v164
	ds_read_b128 v[178:181], v164 offset:1024
	ds_read_b128 v[182:185], v164 offset:2048
	ds_read_b128 v[186:189], v164 offset:3072
	ds_read_b128 v[192:195], v164 offset:4096
	ds_read_b128 v[196:199], v164 offset:5120
	ds_read_b128 v[200:203], v164 offset:6144
	ds_read_b128 v[204:207], v164 offset:7168
	global_load_lds_dwordx4 v138, s[98:99]
	s_add_i32 m0, s58, 0xe000
	s_nop 0
	global_load_lds_dwordx4 v142, s[98:99]
	s_waitcnt lgkmcnt(8)
	s_barrier
	s_waitcnt lgkmcnt(0)
	s_setprio 1
	s_waitcnt lgkmcnt(0)
	v_mfma_f32_16x16x32_bf16 v[126:129], v[130:133], v[174:177], v[126:129]
	v_mfma_f32_16x16x32_bf16 v[122:125], v[154:157], v[174:177], v[122:125]
	v_mfma_f32_16x16x32_bf16 v[110:113], v[130:133], v[182:185], v[110:113]
	v_mfma_f32_16x16x32_bf16 v[106:109], v[154:157], v[182:185], v[106:109]
	v_mfma_f32_16x16x32_bf16 v[94:97], v[130:133], v[192:195], v[94:97]
	v_mfma_f32_16x16x32_bf16 v[90:93], v[154:157], v[192:195], v[90:93]
	v_mfma_f32_16x16x32_bf16 v[78:81], v[130:133], v[200:203], v[78:81]
	v_mfma_f32_16x16x32_bf16 v[74:77], v[154:157], v[200:203], v[74:77]
	v_mfma_f32_16x16x32_bf16 v[126:129], v[134:137], v[178:181], v[126:129]
	v_mfma_f32_16x16x32_bf16 v[122:125], v[170:173], v[178:181], v[122:125]
	v_mfma_f32_16x16x32_bf16 v[110:113], v[134:137], v[186:189], v[110:113]
	v_mfma_f32_16x16x32_bf16 v[106:109], v[170:173], v[186:189], v[106:109]
	v_mfma_f32_16x16x32_bf16 v[94:97], v[134:137], v[196:199], v[94:97]
	v_mfma_f32_16x16x32_bf16 v[90:93], v[170:173], v[196:199], v[90:93]
	v_mfma_f32_16x16x32_bf16 v[78:81], v[134:137], v[204:207], v[78:81]
	v_mfma_f32_16x16x32_bf16 v[74:77], v[170:173], v[204:207], v[74:77]
	s_setprio 0
	s_barrier
	s_add_i32 s0, s66, s57
	s_mov_b32 m0, s0
	ds_read_b128 v[208:211], v165
	ds_read_b128 v[212:215], v165 offset:1024
	ds_read_b128 v[216:219], v165 offset:2048
	ds_read_b128 v[220:223], v165 offset:3072
	global_load_lds_dwordx4 v140, s[50:51]
	s_add_i32 m0, s0, 0x2000
	s_nop 0
	global_load_lds_dwordx4 v144, s[50:51]
	s_barrier
	s_waitcnt lgkmcnt(0)
	s_setprio 1
	s_waitcnt lgkmcnt(0)
	v_mfma_f32_16x16x32_bf16 v[118:121], v[208:211], v[174:177], v[118:121]
	v_mfma_f32_16x16x32_bf16 v[114:117], v[216:219], v[174:177], v[114:117]
	v_mfma_f32_16x16x32_bf16 v[102:105], v[208:211], v[182:185], v[102:105]
	v_mfma_f32_16x16x32_bf16 v[98:101], v[216:219], v[182:185], v[98:101]
	v_mfma_f32_16x16x32_bf16 v[86:89], v[208:211], v[192:195], v[86:89]
	v_mfma_f32_16x16x32_bf16 v[82:85], v[216:219], v[192:195], v[82:85]
	v_mfma_f32_16x16x32_bf16 v[70:73], v[208:211], v[200:203], v[70:73]
	v_mfma_f32_16x16x32_bf16 v[66:69], v[216:219], v[200:203], v[66:69]
	v_mfma_f32_16x16x32_bf16 v[118:121], v[212:215], v[178:181], v[118:121]
	v_mfma_f32_16x16x32_bf16 v[114:117], v[220:223], v[178:181], v[114:117]
	v_mfma_f32_16x16x32_bf16 v[102:105], v[212:215], v[186:189], v[102:105]
	v_mfma_f32_16x16x32_bf16 v[98:101], v[220:223], v[186:189], v[98:101]
	v_mfma_f32_16x16x32_bf16 v[86:89], v[212:215], v[196:199], v[86:89]
	v_mfma_f32_16x16x32_bf16 v[82:85], v[220:223], v[196:199], v[82:85]
	v_mfma_f32_16x16x32_bf16 v[70:73], v[212:215], v[204:207], v[70:73]
	v_mfma_f32_16x16x32_bf16 v[66:69], v[220:223], v[204:207], v[66:69]
	s_setprio 0
	s_mov_b32 m0, s58
	s_barrier
	ds_read_b128 v[174:177], v164 offset:16384
	ds_read_b128 v[178:181], v164 offset:17408
	ds_read_b128 v[182:185], v164 offset:18432
	ds_read_b128 v[186:189], v164 offset:19456
	ds_read_b128 v[192:195], v164 offset:20480
	ds_read_b128 v[196:199], v164 offset:21504
	ds_read_b128 v[200:203], v164 offset:22528
	ds_read_b128 v[204:207], v164 offset:23552
	global_load_lds_dwordx4 v138, s[52:53]
	s_mov_b32 m0, s59
	s_nop 0
	global_load_lds_dwordx4 v142, s[52:53]
	s_barrier
	s_waitcnt lgkmcnt(0)
	s_setprio 1
	s_waitcnt lgkmcnt(0)
	v_mfma_f32_16x16x32_bf16 v[62:65], v[130:133], v[174:177], v[62:65]
	v_mfma_f32_16x16x32_bf16 v[58:61], v[154:157], v[174:177], v[58:61]
	v_mfma_f32_16x16x32_bf16 v[46:49], v[130:133], v[182:185], v[46:49]
	v_mfma_f32_16x16x32_bf16 v[42:45], v[154:157], v[182:185], v[42:45]
	v_mfma_f32_16x16x32_bf16 v[30:33], v[130:133], v[192:195], v[30:33]
	v_mfma_f32_16x16x32_bf16 v[26:29], v[154:157], v[192:195], v[26:29]
	v_mfma_f32_16x16x32_bf16 v[14:17], v[130:133], v[200:203], v[14:17]
	v_mfma_f32_16x16x32_bf16 v[10:13], v[154:157], v[200:203], v[10:13]
	v_mfma_f32_16x16x32_bf16 v[62:65], v[134:137], v[178:181], v[62:65]
	v_mfma_f32_16x16x32_bf16 v[58:61], v[170:173], v[178:181], v[58:61]
	v_mfma_f32_16x16x32_bf16 v[46:49], v[134:137], v[186:189], v[46:49]
	v_mfma_f32_16x16x32_bf16 v[42:45], v[170:173], v[186:189], v[42:45]
	v_mfma_f32_16x16x32_bf16 v[30:33], v[134:137], v[196:199], v[30:33]
	v_mfma_f32_16x16x32_bf16 v[26:29], v[170:173], v[196:199], v[26:29]
	v_mfma_f32_16x16x32_bf16 v[14:17], v[134:137], v[204:207], v[14:17]
	v_mfma_f32_16x16x32_bf16 v[10:13], v[170:173], v[204:207], v[10:13]
	s_setprio 0
	s_barrier
	s_add_u32 s0, s50, 0x84000
	s_addc_u32 s1, s51, 0
	s_add_i32 s2, s67, s57
	s_mov_b32 m0, s2
	s_nop 0
	global_load_lds_dwordx4 v140, s[0:1]
	s_add_i32 m0, s2, 0x2000
	s_nop 0
	global_load_lds_dwordx4 v144, s[0:1]
	s_waitcnt vmcnt(6)
	s_barrier
; #define G_STAGE(bufoff, gbase, voff) do { _Pragma("unroll") for (int _i = 0; _i < 2; ++_i) \
;         __builtin_amdgcn_global_load_lds((const unsigned*)((const char*)(gbase) + (voff)[_i]), (LAS unsigned*)(lds + (bufoff) + ldsw + _i * 8192), 16, 0, 0); } while (0)
; #define G_WAIT_V(n) asm volatile("s_waitcnt vmcnt(" #n ")" ::: "memory")
; #define G_WAIT_L(n) asm volatile("s_waitcnt lgkmcnt(" #n ")" ::: "memory")
; #define G_BAR __builtin_amdgcn_s_barrier()
; #define G_SCHED __builtin_amdgcn_sched_barrier(0)
; template <int MODE  , class Epi, class Sched>
; __device__ __forceinline__ void gemm_phase(LAS unsigned char* lds, const GemmDesc g, const Sched& S, const Epi& E) {
;     ...
;             G_WAIT_V(6); G_BAR; G_MMA(1, 1, At, B1); G_BAR;
;             G_LDB(B0, 1, 0); G_SCHED; G_LDA(At, 1, 0); G_STAGE(G_SA(0, 1), a2 + hstepA, voffA);
;             G_WAIT_L(8); G_BAR; G_WAIT_L(0); G_MMA(0, 0, At, B0); G_BAR; G_SCHED;
;             G_LDB(B1, 1, 1); G_STAGE(G_SB(1, 0), b3, voffB);
;             G_BAR; G_WAIT_L(0); G_MMA(0, 1, At, B1); G_BAR;
	s_setprio 1
	v_mfma_f32_16x16x32_bf16 v[54:57], v[208:211], v[174:177], v[54:57]
	v_mfma_f32_16x16x32_bf16 v[50:53], v[216:219], v[174:177], v[50:53]
	v_mfma_f32_16x16x32_bf16 v[38:41], v[208:211], v[182:185], v[38:41]
	v_mfma_f32_16x16x32_bf16 v[34:37], v[216:219], v[182:185], v[34:37]
	v_mfma_f32_16x16x32_bf16 v[22:25], v[208:211], v[192:195], v[22:25]
	v_mfma_f32_16x16x32_bf16 v[18:21], v[216:219], v[192:195], v[18:21]
	v_mfma_f32_16x16x32_bf16 v[6:9], v[208:211], v[200:203], v[6:9]
	v_mfma_f32_16x16x32_bf16 v[2:5], v[216:219], v[200:203], v[2:5]
	v_mfma_f32_16x16x32_bf16 v[54:57], v[212:215], v[178:181], v[54:57]
	v_mfma_f32_16x16x32_bf16 v[50:53], v[220:223], v[178:181], v[50:53]
	v_mfma_f32_16x16x32_bf16 v[38:41], v[212:215], v[186:189], v[38:41]
	v_mfma_f32_16x16x32_bf16 v[34:37], v[220:223], v[186:189], v[34:37]
	v_mfma_f32_16x16x32_bf16 v[22:25], v[212:215], v[196:199], v[22:25]
	v_mfma_f32_16x16x32_bf16 v[18:21], v[220:223], v[196:199], v[18:21]
	v_mfma_f32_16x16x32_bf16 v[6:9], v[212:215], v[204:207], v[6:9]
	v_mfma_f32_16x16x32_bf16 v[2:5], v[220:223], v[204:207], v[2:5]
	s_setprio 0
	s_add_i32 s2, 0, 0x18000
	v_add_u32_e32 v146, s2, v160
	s_barrier
	ds_read_b128 v[130:133], v146
	ds_read_b128 v[134:137], v146 offset:1024
	ds_read_b128 v[154:157], v146 offset:2048
	ds_read_b128 v[170:173], v146 offset:3072
	s_add_u32 s0, s52, 0x84000
	s_addc_u32 s1, s53, 0
	s_mov_b32 m0, s60
	ds_read_b128 v[174:177], v164 offset:32768
	ds_read_b128 v[178:181], v164 offset:33792
	ds_read_b128 v[182:185], v164 offset:34816
	ds_read_b128 v[186:189], v164 offset:35840
	ds_read_b128 v[192:195], v164 offset:36864
	ds_read_b128 v[196:199], v164 offset:37888
	ds_read_b128 v[200:203], v164 offset:38912
	ds_read_b128 v[204:207], v164 offset:39936
	global_load_lds_dwordx4 v138, s[0:1]
	s_mov_b32 m0, s61
	s_nop 0
	global_load_lds_dwordx4 v142, s[0:1]
	s_waitcnt lgkmcnt(8)
	s_barrier
	s_waitcnt lgkmcnt(0)
	s_setprio 1
	s_waitcnt lgkmcnt(0)
	v_mfma_f32_16x16x32_bf16 v[126:129], v[130:133], v[174:177], v[126:129]
	v_mfma_f32_16x16x32_bf16 v[122:125], v[154:157], v[174:177], v[122:125]
	v_mfma_f32_16x16x32_bf16 v[110:113], v[130:133], v[182:185], v[110:113]
	v_mfma_f32_16x16x32_bf16 v[106:109], v[154:157], v[182:185], v[106:109]
	v_mfma_f32_16x16x32_bf16 v[94:97], v[130:133], v[192:195], v[94:97]
	v_mfma_f32_16x16x32_bf16 v[90:93], v[154:157], v[192:195], v[90:93]
	v_mfma_f32_16x16x32_bf16 v[78:81], v[130:133], v[200:203], v[78:81]
	v_mfma_f32_16x16x32_bf16 v[74:77], v[154:157], v[200:203], v[74:77]
	v_mfma_f32_16x16x32_bf16 v[126:129], v[134:137], v[178:181], v[126:129]
	v_mfma_f32_16x16x32_bf16 v[122:125], v[170:173], v[178:181], v[122:125]
	v_mfma_f32_16x16x32_bf16 v[110:113], v[134:137], v[186:189], v[110:113]
	v_mfma_f32_16x16x32_bf16 v[106:109], v[170:173], v[186:189], v[106:109]
	v_mfma_f32_16x16x32_bf16 v[94:97], v[134:137], v[196:199], v[94:97]
	v_mfma_f32_16x16x32_bf16 v[90:93], v[170:173], v[196:199], v[90:93]
	v_mfma_f32_16x16x32_bf16 v[78:81], v[134:137], v[204:207], v[78:81]
	v_mfma_f32_16x16x32_bf16 v[74:77], v[170:173], v[204:207], v[74:77]
	s_setprio 0
	s_barrier
	s_add_i32 s3, 0, 0x1c000
	s_add_i32 s0, s2, s57
	v_add_u32_e32 v146, s3, v160
	s_add_u32 s98, s50, 0x80
	s_addc_u32 s99, s51, 0
	s_mov_b32 m0, s0
	ds_read_b128 v[208:211], v146
	ds_read_b128 v[212:215], v146 offset:1024
	ds_read_b128 v[216:219], v146 offset:2048
	ds_read_b128 v[220:223], v146 offset:3072
	global_load_lds_dwordx4 v140, s[98:99]
	s_add_i32 m0, s0, 0x2000
	s_nop 0
	global_load_lds_dwordx4 v144, s[98:99]
	s_barrier
; #define G_STAGE(bufoff, gbase, voff) do { _Pragma("unroll") for (int _i = 0; _i < 2; ++_i) \
;         __builtin_amdgcn_global_load_lds((const unsigned*)((const char*)(gbase) + (voff)[_i]), (LAS unsigned*)(lds + (bufoff) + ldsw + _i * 8192), 16, 0, 0); } while (0)
; #define G_WAIT_V(n) asm volatile("s_waitcnt vmcnt(" #n ")" ::: "memory")
; #define G_WAIT_L(n) asm volatile("s_waitcnt lgkmcnt(" #n ")" ::: "memory")
; #define G_BAR __builtin_amdgcn_s_barrier()
; #define G_SCHED __builtin_amdgcn_sched_barrier(0)
; template <int MODE  , class Epi, class Sched>
; __device__ __forceinline__ void gemm_phase(LAS unsigned char* lds, const GemmDesc g, const Sched& S, const Epi& E) {
;     ...
;             G_LDB(B1, 1, 1); G_STAGE(G_SB(1, 0), b3, voffB);
;             G_BAR; G_WAIT_L(0); G_MMA(0, 1, At, B1); G_BAR;
;             G_LDA(At, 1, 1); G_STAGE(G_SA(1, 0), a3, voffA);
;             G_BAR; G_WAIT_L(0); G_MMA(1, 0, At, B0); G_BAR; G_SCHED;
;             G_STAGE(G_SB(1, 1), b3 + hstepB, voffB);
;             G_WAIT_V(6); G_BAR; G_MMA(1, 1, At, B1); G_BAR;
;         }
	s_waitcnt lgkmcnt(0)
	s_setprio 1
	s_waitcnt lgkmcnt(0)
	v_mfma_f32_16x16x32_bf16 v[118:121], v[208:211], v[174:177], v[118:121]
	v_mfma_f32_16x16x32_bf16 v[114:117], v[216:219], v[174:177], v[114:117]
	v_mfma_f32_16x16x32_bf16 v[102:105], v[208:211], v[182:185], v[102:105]
	v_mfma_f32_16x16x32_bf16 v[98:101], v[216:219], v[182:185], v[98:101]
	v_mfma_f32_16x16x32_bf16 v[86:89], v[208:211], v[192:195], v[86:89]
	v_mfma_f32_16x16x32_bf16 v[82:85], v[216:219], v[192:195], v[82:85]
	v_mfma_f32_16x16x32_bf16 v[70:73], v[208:211], v[200:203], v[70:73]
	v_mfma_f32_16x16x32_bf16 v[66:69], v[216:219], v[200:203], v[66:69]
	v_mfma_f32_16x16x32_bf16 v[118:121], v[212:215], v[178:181], v[118:121]
	v_mfma_f32_16x16x32_bf16 v[114:117], v[220:223], v[178:181], v[114:117]
	v_mfma_f32_16x16x32_bf16 v[102:105], v[212:215], v[186:189], v[102:105]
	v_mfma_f32_16x16x32_bf16 v[98:101], v[220:223], v[186:189], v[98:101]
	v_mfma_f32_16x16x32_bf16 v[86:89], v[212:215], v[196:199], v[86:89]
	v_mfma_f32_16x16x32_bf16 v[82:85], v[220:223], v[196:199], v[82:85]
	v_mfma_f32_16x16x32_bf16 v[70:73], v[212:215], v[204:207], v[70:73]
	v_mfma_f32_16x16x32_bf16 v[66:69], v[220:223], v[204:207], v[66:69]
	s_setprio 0
	s_mov_b32 m0, s64
	s_add_u32 s98, s52, 0x80
	s_addc_u32 s99, s53, 0
	s_barrier
	ds_read_b128 v[174:177], v164 offset:49152
	ds_read_b128 v[178:181], v164 offset:50176
	ds_read_b128 v[182:185], v164 offset:51200
	ds_read_b128 v[186:189], v164 offset:52224
	ds_read_b128 v[192:195], v164 offset:53248
	ds_read_b128 v[196:199], v164 offset:54272
	ds_read_b128 v[200:203], v164 offset:55296
	ds_read_b128 v[204:207], v164 offset:56320
	global_load_lds_dwordx4 v138, s[98:99]
	s_mov_b32 m0, s65
	s_nop 0
	global_load_lds_dwordx4 v142, s[98:99]
	s_barrier
	s_waitcnt lgkmcnt(0)
	s_setprio 1
	s_waitcnt lgkmcnt(0)
	v_mfma_f32_16x16x32_bf16 v[62:65], v[130:133], v[174:177], v[62:65]
	v_mfma_f32_16x16x32_bf16 v[58:61], v[154:157], v[174:177], v[58:61]
	v_mfma_f32_16x16x32_bf16 v[46:49], v[130:133], v[182:185], v[46:49]
	v_mfma_f32_16x16x32_bf16 v[42:45], v[154:157], v[182:185], v[42:45]
	v_mfma_f32_16x16x32_bf16 v[30:33], v[130:133], v[192:195], v[30:33]
	v_mfma_f32_16x16x32_bf16 v[26:29], v[154:157], v[192:195], v[26:29]
	v_mfma_f32_16x16x32_bf16 v[14:17], v[130:133], v[200:203], v[14:17]
	v_mfma_f32_16x16x32_bf16 v[10:13], v[154:157], v[200:203], v[10:13]
	v_mfma_f32_16x16x32_bf16 v[62:65], v[134:137], v[178:181], v[62:65]
	v_mfma_f32_16x16x32_bf16 v[58:61], v[170:173], v[178:181], v[58:61]
	v_mfma_f32_16x16x32_bf16 v[46:49], v[134:137], v[186:189], v[46:49]
	v_mfma_f32_16x16x32_bf16 v[42:45], v[170:173], v[186:189], v[42:45]
	v_mfma_f32_16x16x32_bf16 v[30:33], v[134:137], v[196:199], v[30:33]
	v_mfma_f32_16x16x32_bf16 v[26:29], v[170:173], v[196:199], v[26:29]
	v_mfma_f32_16x16x32_bf16 v[14:17], v[134:137], v[204:207], v[14:17]
	v_mfma_f32_16x16x32_bf16 v[10:13], v[170:173], v[204:207], v[10:13]
	s_setprio 0
	s_barrier
	s_add_u32 s0, s50, 0x84080
	s_addc_u32 s1, s51, 0
	s_add_i32 s2, s3, s57
	s_mov_b32 m0, s2
	s_nop 0
	global_load_lds_dwordx4 v140, s[0:1]
	s_add_i32 m0, s2, 0x2000
	s_nop 0
	global_load_lds_dwordx4 v144, s[0:1]
	s_waitcnt vmcnt(6)
	s_barrier
	s_setprio 1
	v_mfma_f32_16x16x32_bf16 v[54:57], v[208:211], v[174:177], v[54:57]
	s_add_i32 s87, s87, 2
	s_add_u32 s85, s85, 0x100
	s_addc_u32 s86, s86, 0
	s_cmp_gt_u32 s87, 29
	s_mov_b64 s[2:3], s[4:5]
	v_mfma_f32_16x16x32_bf16 v[50:53], v[216:219], v[174:177], v[50:53]
	v_mfma_f32_16x16x32_bf16 v[38:41], v[208:211], v[182:185], v[38:41]
	v_mfma_f32_16x16x32_bf16 v[34:37], v[216:219], v[182:185], v[34:37]
	v_mfma_f32_16x16x32_bf16 v[22:25], v[208:211], v[192:195], v[22:25]
	v_mfma_f32_16x16x32_bf16 v[18:21], v[216:219], v[192:195], v[18:21]
	v_mfma_f32_16x16x32_bf16 v[6:9], v[208:211], v[200:203], v[6:9]
	v_mfma_f32_16x16x32_bf16 v[2:5], v[216:219], v[200:203], v[2:5]
	v_mfma_f32_16x16x32_bf16 v[54:57], v[212:215], v[178:181], v[54:57]
	v_mfma_f32_16x16x32_bf16 v[50:53], v[220:223], v[178:181], v[50:53]
	v_mfma_f32_16x16x32_bf16 v[38:41], v[212:215], v[186:189], v[38:41]
	v_mfma_f32_16x16x32_bf16 v[34:37], v[220:223], v[186:189], v[34:37]
	v_mfma_f32_16x16x32_bf16 v[22:25], v[212:215], v[196:199], v[22:25]
	v_mfma_f32_16x16x32_bf16 v[18:21], v[220:223], v[196:199], v[18:21]
	v_mfma_f32_16x16x32_bf16 v[6:9], v[212:215], v[204:207], v[6:9]
	v_mfma_f32_16x16x32_bf16 v[2:5], v[220:223], v[204:207], v[2:5]
	s_setprio 0
	s_cbranch_scc1 .Lkdone_s1a
	s_barrier
	s_branch .LBB0_1017
